# GEMM1 accumulators zeroed inside the store-bound epilogue (zero block only for the first unit); GLA stage-C exponentials issued behind stage-E MFMAs with hoisted cumsum reads
# baseline (speedup 1.0000x reference)
.LBB0_117:
	s_and_b64 vcc, exec, s[10:11]
	s_cbranch_vccz .LBB0_196
	s_cmpk_gt_i32 s2, 0x9ff
	v_readfirstlane_b32 s1, v0
	s_cbranch_scc1 .LBB0_134
	v_lshrrev_b32_e32 v1, 5, v0
	s_waitcnt vmcnt(8)
	v_lshrrev_b32_e32 v3, 1, v0
	v_and_b32_e32 v1, 4, v1
	v_bfe_u32 v2, v0, 2, 2
	v_and_b32_e32 v14, 24, v3
	v_or3_b32 v1, v1, v2, v14
	v_lshlrev_b32_e32 v2, 4, v0
	v_or_b32_e32 v10, 0x2000, v2
	v_lshrrev_b32_e32 v3, 7, v10
	s_movk_i32 s0, 0x60
	v_and_or_b32 v4, v3, s0, v1
	v_bfe_u32 v13, v0, 2, 4
	s_movk_i32 s0, 0x70
	s_waitcnt lgkmcnt(0)
	s_ashr_i32 s45, s2, 31
	v_and_or_b32 v3, v3, s0, v13
	s_lshr_b32 s0, s45, 29
	s_add_i32 s0, s2, s0
	s_lshr_b32 s8, s1, 6
	s_ashr_i32 s6, s0, 3
	s_and_b32 s0, s0, -8
	s_lshr_b32 s10, s1, 8
	s_lshl_b32 s44, s8, 10
	s_sub_i32 s0, s2, s0
	s_cmp_lt_i32 s0, 0
	s_movk_i32 s46, 0x141
	s_cselect_b32 s7, s46, 0x140
	s_mul_i32 s0, s0, s7
	s_add_i32 s0, s0, s6
	s_mul_hi_i32 s6, s0, 0x66666667
	s_lshr_b32 s7, s6, 31
	s_ashr_i32 s6, s6, 5
	s_add_i32 s6, s6, s7
	s_lshl_b32 s7, s6, 3
	s_mulk_i32 s6, 0x50
	s_sub_i32 s6, s0, s6
	s_bfe_i32 s0, s6, 0x80000
	s_bfe_u32 s0, s0, 0x3000c
	s_add_i32 s9, s6, s0
	s_bfe_i32 s0, s9, 0x80000
	s_and_b32 s9, s9, 0xf8
	s_sub_i32 s6, s6, s9
	s_sext_i32_i16 s0, s0
	s_sext_i32_i8 s6, s6
	v_and_b32_e32 v5, 32, v0
	s_lshr_b32 s0, s0, 3
	s_add_i32 s36, s7, s6
	v_bitop3_b32 v11, v2, v5, 48 bitop3:0x6c
	v_and_b32_e32 v12, 64, v0
	s_ashr_i32 s37, s36, 31
	s_bfe_i64 s[12:13], s[0:1], 0x100000
	v_or_b32_e32 v2, v11, v12
	s_lshl_b64 s[6:7], s[36:37], 19
	s_lshl_b64 s[12:13], s[12:13], 19
	v_lshl_or_b32 v132, v3, 11, v2
	v_lshrrev_b32_e32 v3, 3, v0
	s_add_u32 s40, s72, s12
	v_and_or_b32 v1, v3, 32, v1
	s_addc_u32 s41, s73, s13
	s_add_i32 s47, s44, 0
	v_lshl_or_b32 v134, v1, 11, v2
	s_add_i32 m0, s47, 0x10000
	v_lshl_or_b32 v130, v4, 11, v2
	global_load_lds_dwordx4 v134, s[40:41]
	s_add_i32 m0, s47, 0x12000
	s_add_u32 s12, s40, 0x40000
	global_load_lds_dwordx4 v130, s[40:41]
	s_addc_u32 s13, s41, 0
	s_add_i32 m0, s47, 0x14000
	v_and_or_b32 v1, v3, 48, v13
	global_load_lds_dwordx4 v134, s[12:13]
	s_add_i32 m0, s47, 0x16000
	s_add_u32 s38, s16, s6
	s_addc_u32 s39, s17, s7
	s_add_i32 s50, s47, 0x2000
	v_lshl_or_b32 v136, v1, 11, v2
	global_load_lds_dwordx4 v130, s[12:13]
	s_mov_b32 m0, s47
	s_add_u32 s6, s38, 0x40000
	global_load_lds_dwordx4 v136, s[38:39]
	s_mov_b32 m0, s50
	s_addc_u32 s7, s39, 0
	s_add_i32 s51, s47, 0x4000
	global_load_lds_dwordx4 v132, s[38:39]
	s_mov_b32 m0, s51
	s_add_i32 s52, s47, 0x6000
	global_load_lds_dwordx4 v136, s[6:7]
	s_mov_b32 m0, s52
	v_mov_b32_e32 v135, 0
	global_load_lds_dwordx4 v132, s[6:7]
	v_mov_b32_e32 v131, v135
	v_mov_b32_e32 v137, v135
	v_mov_b32_e32 v133, v135
	s_cmp_eq_u32 s10, 1
	s_mov_b32 s53, 0
	s_mov_b32 s98, 0
	v_lshl_add_u64 v[8:9], s[40:41], 0, v[134:135]
	v_lshl_add_u64 v[6:7], s[40:41], 0, v[130:131]
	v_lshl_add_u64 v[2:3], s[38:39], 0, v[136:137]
	s_cselect_b64 s[6:7], -1, 0
	s_cmp_lg_u32 s10, 1
	v_lshl_add_u64 v[4:5], s[38:39], 0, v[132:133]
	s_cbranch_scc1 .LBB0_121
	s_barrier

.LBB0_126:
	s_ashr_i32 s27, s26, 31
	s_lshl_b64 s[28:29], s[26:27], 19
	s_add_u32 s28, s16, s28
	s_addc_u32 s29, s17, s29
	s_and_b64 s[30:31], s[0:1], exec
	s_cselect_b32 s27, s29, s39
	s_cselect_b32 s85, s28, s38
	s_ashr_i32 s25, s24, 31
	s_lshl_b64 s[30:31], s[24:25], 19
	s_add_u32 s30, s72, s30
	s_addc_u32 s31, s73, s31
	s_and_b64 s[42:43], s[0:1], exec
	s_cselect_b32 s25, s31, s41
	s_cselect_b32 s86, s30, s40
	s_add_u32 s38, s38, 0x40080
	s_addc_u32 s39, s39, 0
	s_add_u32 s87, s40, 0x100
	s_addc_u32 s88, s41, 0
	s_mov_b32 s89, -2
	s_cmp_lg_u32 s98, 0
	s_cbranch_scc1 .Lg1_zeroed
	v_mov_b32_e32 v2, 0
	v_mov_b32_e32 v3, v2
	v_mov_b32_e32 v4, v2
	v_mov_b32_e32 v5, v2
	v_mov_b32_e32 v6, v2
	v_mov_b32_e32 v7, v2
	v_mov_b32_e32 v8, v2
	v_mov_b32_e32 v9, v2
	v_mov_b32_e32 v10, v2
	v_mov_b32_e32 v11, v2
	v_mov_b32_e32 v12, v2
	v_mov_b32_e32 v13, v2
	v_mov_b32_e32 v14, v2
	v_mov_b32_e32 v15, v2
	v_mov_b32_e32 v16, v2
	v_mov_b32_e32 v17, v2
	v_mov_b32_e32 v18, v2
	v_mov_b32_e32 v19, v2
	v_mov_b32_e32 v20, v2
	v_mov_b32_e32 v21, v2
	v_mov_b32_e32 v22, v2
	v_mov_b32_e32 v23, v2
	v_mov_b32_e32 v24, v2
	v_mov_b32_e32 v25, v2
	v_mov_b32_e32 v26, v2
	v_mov_b32_e32 v27, v2
	v_mov_b32_e32 v28, v2
	v_mov_b32_e32 v29, v2
	v_mov_b32_e32 v30, v2
	v_mov_b32_e32 v31, v2
	v_mov_b32_e32 v32, v2
	v_mov_b32_e32 v33, v2
	v_mov_b32_e32 v50, v2
	v_mov_b32_e32 v51, v2
	v_mov_b32_e32 v52, v2
	v_mov_b32_e32 v53, v2
	v_mov_b32_e32 v58, v2
	v_mov_b32_e32 v59, v2
	v_mov_b32_e32 v60, v2
	v_mov_b32_e32 v61, v2
	v_mov_b32_e32 v66, v2
	v_mov_b32_e32 v67, v2
	v_mov_b32_e32 v68, v2
	v_mov_b32_e32 v69, v2
	v_mov_b32_e32 v74, v2
	v_mov_b32_e32 v75, v2
	v_mov_b32_e32 v76, v2
	v_mov_b32_e32 v77, v2
	v_mov_b32_e32 v82, v2
	v_mov_b32_e32 v83, v2
	v_mov_b32_e32 v84, v2
	v_mov_b32_e32 v85, v2
	v_mov_b32_e32 v86, v2
	v_mov_b32_e32 v87, v2
	v_mov_b32_e32 v88, v2
	v_mov_b32_e32 v89, v2
	v_mov_b32_e32 v90, v2
	v_mov_b32_e32 v91, v2
	v_mov_b32_e32 v92, v2
	v_mov_b32_e32 v93, v2
	v_mov_b32_e32 v94, v2
	v_mov_b32_e32 v95, v2
	v_mov_b32_e32 v96, v2
	v_mov_b32_e32 v97, v2
	v_mov_b32_e32 v34, v2
	v_mov_b32_e32 v35, v2
	v_mov_b32_e32 v36, v2
	v_mov_b32_e32 v37, v2
	v_mov_b32_e32 v38, v2
	v_mov_b32_e32 v39, v2
	v_mov_b32_e32 v40, v2
	v_mov_b32_e32 v41, v2
	v_mov_b32_e32 v42, v2
	v_mov_b32_e32 v43, v2
	v_mov_b32_e32 v44, v2
	v_mov_b32_e32 v45, v2
	v_mov_b32_e32 v46, v2
	v_mov_b32_e32 v47, v2
	v_mov_b32_e32 v48, v2
	v_mov_b32_e32 v49, v2
	v_mov_b32_e32 v54, v2
	v_mov_b32_e32 v55, v2
	v_mov_b32_e32 v56, v2
	v_mov_b32_e32 v57, v2
	v_mov_b32_e32 v62, v2
	v_mov_b32_e32 v63, v2
	v_mov_b32_e32 v64, v2
	v_mov_b32_e32 v65, v2
	v_mov_b32_e32 v70, v2
	v_mov_b32_e32 v71, v2
	v_mov_b32_e32 v72, v2
	v_mov_b32_e32 v73, v2
	v_mov_b32_e32 v78, v2
	v_mov_b32_e32 v79, v2
	v_mov_b32_e32 v80, v2
	v_mov_b32_e32 v81, v2
	v_mov_b32_e32 v98, v2
	v_mov_b32_e32 v99, v2
	v_mov_b32_e32 v100, v2
	v_mov_b32_e32 v101, v2
	v_mov_b32_e32 v102, v2
	v_mov_b32_e32 v103, v2
	v_mov_b32_e32 v104, v2
	v_mov_b32_e32 v105, v2
	v_mov_b32_e32 v106, v2
	v_mov_b32_e32 v107, v2
	v_mov_b32_e32 v108, v2
	v_mov_b32_e32 v109, v2
	v_mov_b32_e32 v110, v2
	v_mov_b32_e32 v111, v2
	v_mov_b32_e32 v112, v2
	v_mov_b32_e32 v113, v2
	v_mov_b32_e32 v114, v2
	v_mov_b32_e32 v115, v2
	v_mov_b32_e32 v116, v2
	v_mov_b32_e32 v117, v2
	v_mov_b32_e32 v118, v2
	v_mov_b32_e32 v119, v2
	v_mov_b32_e32 v120, v2
	v_mov_b32_e32 v121, v2
	v_mov_b32_e32 v122, v2
	v_mov_b32_e32 v123, v2
	v_mov_b32_e32 v124, v2
	v_mov_b32_e32 v125, v2
	v_mov_b32_e32 v126, v2
	v_mov_b32_e32 v127, v2
	v_mov_b32_e32 v128, v2
	v_mov_b32_e32 v129, v2
.Lg1_zeroed:
.LBB0_127:
	ds_read_b128 v[154:157], v151
	ds_read_b128 v[158:161], v151 offset:1024
	ds_read_b128 v[162:165], v151 offset:2048
	ds_read_b128 v[166:169], v151 offset:3072
	ds_read_b128 v[170:173], v152
	ds_read_b128 v[174:177], v152 offset:1024
	ds_read_b128 v[178:181], v152 offset:2048
	ds_read_b128 v[182:185], v152 offset:3072
	s_add_u32 s40, s38, 0xfffc0080
	s_addc_u32 s41, s39, -1
	s_cmp_eq_u32 s89, 12
	s_cselect_b32 s43, s27, s41
	s_cselect_b32 s42, s85, s40
	s_cselect_b32 s41, s25, s88
	s_cselect_b32 s40, s86, s87
	v_lshl_add_u64 v[218:219], s[38:39], 0, v[140:141]
	s_add_i32 m0, s47, 0xc000
	ds_read_b128 v[186:189], v153
	ds_read_b128 v[190:193], v153 offset:1024
	ds_read_b128 v[194:197], v153 offset:2048
	ds_read_b128 v[198:201], v153 offset:3072
	ds_read_b128 v[202:205], v153 offset:4096
	ds_read_b128 v[206:209], v153 offset:5120
	ds_read_b128 v[210:213], v153 offset:6144
	ds_read_b128 v[214:217], v153 offset:7168
	global_load_lds_dwordx4 v[218:219], off
	v_lshl_add_u64 v[218:219], s[38:39], 0, v[142:143]
	s_add_i32 m0, s47, 0xe000
	s_nop 0
	global_load_lds_dwordx4 v[218:219], off
	s_waitcnt vmcnt(8)
	s_waitcnt lgkmcnt(0)
	s_barrier
	s_setprio 1
	s_waitcnt lgkmcnt(0)
	v_mfma_f32_16x16x32_bf16 v[126:129], v[154:157], v[186:189], v[126:129]
	v_mfma_f32_16x16x32_bf16 v[122:125], v[162:165], v[186:189], v[122:125]
	v_mfma_f32_16x16x32_bf16 v[118:121], v[154:157], v[194:197], v[118:121]
	v_mfma_f32_16x16x32_bf16 v[114:117], v[162:165], v[194:197], v[114:117]
	v_mfma_f32_16x16x32_bf16 v[110:113], v[154:157], v[202:205], v[110:113]
	v_mfma_f32_16x16x32_bf16 v[106:109], v[162:165], v[202:205], v[106:109]
	v_mfma_f32_16x16x32_bf16 v[102:105], v[154:157], v[210:213], v[102:105]
	v_mfma_f32_16x16x32_bf16 v[98:101], v[162:165], v[210:213], v[98:101]
	v_mfma_f32_16x16x32_bf16 v[126:129], v[158:161], v[190:193], v[126:129]
	v_mfma_f32_16x16x32_bf16 v[122:125], v[166:169], v[190:193], v[122:125]
	v_mfma_f32_16x16x32_bf16 v[118:121], v[158:161], v[198:201], v[118:121]
	v_mfma_f32_16x16x32_bf16 v[114:117], v[166:169], v[198:201], v[114:117]
	v_mfma_f32_16x16x32_bf16 v[110:113], v[158:161], v[206:209], v[110:113]
	v_mfma_f32_16x16x32_bf16 v[106:109], v[166:169], v[206:209], v[106:109]
	v_mfma_f32_16x16x32_bf16 v[102:105], v[158:161], v[214:217], v[102:105]
	v_mfma_f32_16x16x32_bf16 v[98:101], v[166:169], v[214:217], v[98:101]
	s_setprio 0
	s_setprio 1
	v_mfma_f32_16x16x32_bf16 v[78:81], v[170:173], v[186:189], v[78:81]
	v_mfma_f32_16x16x32_bf16 v[70:73], v[178:181], v[186:189], v[70:73]
	v_mfma_f32_16x16x32_bf16 v[62:65], v[170:173], v[194:197], v[62:65]
	v_mfma_f32_16x16x32_bf16 v[54:57], v[178:181], v[194:197], v[54:57]
	v_mfma_f32_16x16x32_bf16 v[46:49], v[170:173], v[202:205], v[46:49]
	v_mfma_f32_16x16x32_bf16 v[42:45], v[178:181], v[202:205], v[42:45]
	v_mfma_f32_16x16x32_bf16 v[38:41], v[170:173], v[210:213], v[38:41]
	v_mfma_f32_16x16x32_bf16 v[34:37], v[178:181], v[210:213], v[34:37]
	v_mfma_f32_16x16x32_bf16 v[78:81], v[174:177], v[190:193], v[78:81]
	v_mfma_f32_16x16x32_bf16 v[70:73], v[182:185], v[190:193], v[70:73]
	v_mfma_f32_16x16x32_bf16 v[62:65], v[174:177], v[198:201], v[62:65]
	v_mfma_f32_16x16x32_bf16 v[54:57], v[182:185], v[198:201], v[54:57]
	v_mfma_f32_16x16x32_bf16 v[46:49], v[174:177], v[206:209], v[46:49]
	v_mfma_f32_16x16x32_bf16 v[42:45], v[182:185], v[206:209], v[42:45]
	v_mfma_f32_16x16x32_bf16 v[38:41], v[174:177], v[214:217], v[38:41]
	v_mfma_f32_16x16x32_bf16 v[34:37], v[182:185], v[214:217], v[34:37]
	s_setprio 0
	s_barrier
	s_add_i32 s90, s83, s44
	v_lshl_add_u64 v[218:219], s[40:41], 0, v[134:135]
	s_mov_b32 m0, s90
	ds_read_b128 v[186:189], v153 offset:16384
	ds_read_b128 v[190:193], v153 offset:17408
	ds_read_b128 v[194:197], v153 offset:18432
	ds_read_b128 v[198:201], v153 offset:19456
	ds_read_b128 v[202:205], v153 offset:20480
	ds_read_b128 v[206:209], v153 offset:21504
	ds_read_b128 v[210:213], v153 offset:22528
	ds_read_b128 v[214:217], v153 offset:23552
	global_load_lds_dwordx4 v[218:219], off
	s_add_i32 m0, s90, 0x2000
	s_add_u32 s90, s40, 0x40000
	v_lshl_add_u64 v[220:221], s[40:41], 0, v[130:131]
	s_addc_u32 s91, s41, 0
	s_add_i32 s92, s84, s44
	global_load_lds_dwordx4 v[220:221], off
	v_lshl_add_u64 v[222:223], s[90:91], 0, v[134:135]
	s_mov_b32 m0, s92
	v_lshl_add_u64 v[224:225], s[42:43], 0, v[132:133]
	global_load_lds_dwordx4 v[222:223], off
	v_lshl_add_u64 v[222:223], s[90:91], 0, v[130:131]
	s_add_i32 m0, s92, 0x2000
	s_nop 0
	global_load_lds_dwordx4 v[222:223], off
	v_lshl_add_u64 v[222:223], s[42:43], 0, v[136:137]
	s_mov_b32 m0, s47
	s_nop 0
	global_load_lds_dwordx4 v[222:223], off
	s_mov_b32 m0, s50
	s_nop 0
	global_load_lds_dwordx4 v[224:225], off
	s_waitcnt vmcnt(8)
	s_waitcnt lgkmcnt(0)
	s_barrier
	s_setprio 1
	s_waitcnt lgkmcnt(0)
	v_mfma_f32_16x16x32_bf16 v[94:97], v[154:157], v[186:189], v[94:97]
	v_mfma_f32_16x16x32_bf16 v[90:93], v[162:165], v[186:189], v[90:93]
	v_mfma_f32_16x16x32_bf16 v[86:89], v[154:157], v[194:197], v[86:89]
	v_mfma_f32_16x16x32_bf16 v[82:85], v[162:165], v[194:197], v[82:85]
	v_mfma_f32_16x16x32_bf16 v[74:77], v[154:157], v[202:205], v[74:77]
	v_mfma_f32_16x16x32_bf16 v[66:69], v[162:165], v[202:205], v[66:69]
	v_mfma_f32_16x16x32_bf16 v[58:61], v[154:157], v[210:213], v[58:61]
	v_mfma_f32_16x16x32_bf16 v[50:53], v[162:165], v[210:213], v[50:53]
	v_mfma_f32_16x16x32_bf16 v[94:97], v[158:161], v[190:193], v[94:97]
	v_mfma_f32_16x16x32_bf16 v[90:93], v[166:169], v[190:193], v[90:93]
	v_mfma_f32_16x16x32_bf16 v[86:89], v[158:161], v[198:201], v[86:89]
	v_mfma_f32_16x16x32_bf16 v[82:85], v[166:169], v[198:201], v[82:85]
	v_mfma_f32_16x16x32_bf16 v[74:77], v[158:161], v[206:209], v[74:77]
	v_mfma_f32_16x16x32_bf16 v[66:69], v[166:169], v[206:209], v[66:69]
	v_mfma_f32_16x16x32_bf16 v[58:61], v[158:161], v[214:217], v[58:61]
	v_mfma_f32_16x16x32_bf16 v[50:53], v[166:169], v[214:217], v[50:53]
	s_setprio 0
	s_setprio 1
	v_mfma_f32_16x16x32_bf16 v[30:33], v[170:173], v[186:189], v[30:33]
	v_mfma_f32_16x16x32_bf16 v[26:29], v[178:181], v[186:189], v[26:29]
	v_mfma_f32_16x16x32_bf16 v[22:25], v[170:173], v[194:197], v[22:25]
	v_mfma_f32_16x16x32_bf16 v[18:21], v[178:181], v[194:197], v[18:21]
	v_mfma_f32_16x16x32_bf16 v[14:17], v[170:173], v[202:205], v[14:17]
	v_mfma_f32_16x16x32_bf16 v[10:13], v[178:181], v[202:205], v[10:13]
	v_mfma_f32_16x16x32_bf16 v[6:9], v[170:173], v[210:213], v[6:9]
	v_mfma_f32_16x16x32_bf16 v[2:5], v[178:181], v[210:213], v[2:5]
	v_mfma_f32_16x16x32_bf16 v[30:33], v[174:177], v[190:193], v[30:33]
	v_mfma_f32_16x16x32_bf16 v[26:29], v[182:185], v[190:193], v[26:29]
	v_mfma_f32_16x16x32_bf16 v[22:25], v[174:177], v[198:201], v[22:25]
	v_mfma_f32_16x16x32_bf16 v[18:21], v[182:185], v[198:201], v[18:21]
	v_mfma_f32_16x16x32_bf16 v[14:17], v[174:177], v[206:209], v[14:17]
	v_mfma_f32_16x16x32_bf16 v[10:13], v[182:185], v[206:209], v[10:13]
	v_mfma_f32_16x16x32_bf16 v[6:9], v[174:177], v[214:217], v[6:9]
	v_mfma_f32_16x16x32_bf16 v[2:5], v[182:185], v[214:217], v[2:5]
	s_setprio 0
	s_barrier
	s_add_i32 s90, 0, 0x18000
	s_add_i32 s91, 0, 0x1c000
	v_add_u32_e32 v166, s90, v150
	v_add_u32_e32 v182, s91, v150
	ds_read_b128 v[154:157], v166
	ds_read_b128 v[158:161], v166 offset:1024
	ds_read_b128 v[162:165], v166 offset:2048
	ds_read_b128 v[166:169], v166 offset:3072
	ds_read_b128 v[170:173], v182
	ds_read_b128 v[174:177], v182 offset:1024
	ds_read_b128 v[178:181], v182 offset:2048
	ds_read_b128 v[182:185], v182 offset:3072
	s_add_u32 s42, s42, 0x40000
	s_addc_u32 s43, s43, 0
	s_mov_b32 m0, s51
	v_lshl_add_u64 v[226:227], s[42:43], 0, v[136:137]
	ds_read_b128 v[186:189], v153 offset:32768
	ds_read_b128 v[190:193], v153 offset:33792
	ds_read_b128 v[194:197], v153 offset:34816
	ds_read_b128 v[198:201], v153 offset:35840
	ds_read_b128 v[202:205], v153 offset:36864
	ds_read_b128 v[206:209], v153 offset:37888
	ds_read_b128 v[210:213], v153 offset:38912
	ds_read_b128 v[214:217], v153 offset:39936
	global_load_lds_dwordx4 v[226:227], off
	v_lshl_add_u64 v[226:227], s[42:43], 0, v[132:133]
	s_mov_b32 m0, s52
	s_nop 0
	global_load_lds_dwordx4 v[226:227], off
	s_waitcnt vmcnt(8)
	s_waitcnt lgkmcnt(0)
	s_barrier
	s_setprio 1
	s_waitcnt lgkmcnt(0)
	v_mfma_f32_16x16x32_bf16 v[126:129], v[154:157], v[186:189], v[126:129]
	v_mfma_f32_16x16x32_bf16 v[122:125], v[162:165], v[186:189], v[122:125]
	v_mfma_f32_16x16x32_bf16 v[118:121], v[154:157], v[194:197], v[118:121]
	v_mfma_f32_16x16x32_bf16 v[114:117], v[162:165], v[194:197], v[114:117]
	v_mfma_f32_16x16x32_bf16 v[110:113], v[154:157], v[202:205], v[110:113]
	v_mfma_f32_16x16x32_bf16 v[106:109], v[162:165], v[202:205], v[106:109]
	v_mfma_f32_16x16x32_bf16 v[102:105], v[154:157], v[210:213], v[102:105]
	v_mfma_f32_16x16x32_bf16 v[98:101], v[162:165], v[210:213], v[98:101]
	v_mfma_f32_16x16x32_bf16 v[126:129], v[158:161], v[190:193], v[126:129]
	v_mfma_f32_16x16x32_bf16 v[122:125], v[166:169], v[190:193], v[122:125]
	v_mfma_f32_16x16x32_bf16 v[118:121], v[158:161], v[198:201], v[118:121]
	v_mfma_f32_16x16x32_bf16 v[114:117], v[166:169], v[198:201], v[114:117]
	v_mfma_f32_16x16x32_bf16 v[110:113], v[158:161], v[206:209], v[110:113]
	v_mfma_f32_16x16x32_bf16 v[106:109], v[166:169], v[206:209], v[106:109]
	v_mfma_f32_16x16x32_bf16 v[102:105], v[158:161], v[214:217], v[102:105]
	v_mfma_f32_16x16x32_bf16 v[98:101], v[166:169], v[214:217], v[98:101]
	s_setprio 0
	s_setprio 1
	v_mfma_f32_16x16x32_bf16 v[78:81], v[170:173], v[186:189], v[78:81]
	v_mfma_f32_16x16x32_bf16 v[70:73], v[178:181], v[186:189], v[70:73]
	v_mfma_f32_16x16x32_bf16 v[62:65], v[170:173], v[194:197], v[62:65]
	v_mfma_f32_16x16x32_bf16 v[54:57], v[178:181], v[194:197], v[54:57]
	v_mfma_f32_16x16x32_bf16 v[46:49], v[170:173], v[202:205], v[46:49]
	v_mfma_f32_16x16x32_bf16 v[42:45], v[178:181], v[202:205], v[42:45]
	v_mfma_f32_16x16x32_bf16 v[38:41], v[170:173], v[210:213], v[38:41]
	v_mfma_f32_16x16x32_bf16 v[34:37], v[178:181], v[210:213], v[34:37]
	v_mfma_f32_16x16x32_bf16 v[78:81], v[174:177], v[190:193], v[78:81]
	v_mfma_f32_16x16x32_bf16 v[70:73], v[182:185], v[190:193], v[70:73]
	v_mfma_f32_16x16x32_bf16 v[62:65], v[174:177], v[198:201], v[62:65]
	v_mfma_f32_16x16x32_bf16 v[54:57], v[182:185], v[198:201], v[54:57]
	v_mfma_f32_16x16x32_bf16 v[46:49], v[174:177], v[206:209], v[46:49]
	v_mfma_f32_16x16x32_bf16 v[42:45], v[182:185], v[206:209], v[42:45]
	v_mfma_f32_16x16x32_bf16 v[38:41], v[174:177], v[214:217], v[38:41]
	v_mfma_f32_16x16x32_bf16 v[34:37], v[182:185], v[214:217], v[34:37]
	s_setprio 0
	s_barrier
	s_add_i32 s42, s90, s44
	v_lshl_add_u64 v[218:219], v[218:219], 0, s[8:9]
	s_mov_b32 m0, s42
	ds_read_b128 v[186:189], v153 offset:49152
	ds_read_b128 v[190:193], v153 offset:50176
	ds_read_b128 v[194:197], v153 offset:51200
	ds_read_b128 v[198:201], v153 offset:52224
	ds_read_b128 v[202:205], v153 offset:53248
	ds_read_b128 v[206:209], v153 offset:54272
	ds_read_b128 v[210:213], v153 offset:55296
	ds_read_b128 v[214:217], v153 offset:56320
	global_load_lds_dwordx4 v[218:219], off
	s_add_i32 m0, s42, 0x2000
	s_add_u32 s40, s40, 0x40080
	v_lshl_add_u64 v[218:219], v[220:221], 0, s[8:9]
	s_addc_u32 s41, s41, 0
	s_add_i32 s42, s91, s44
	global_load_lds_dwordx4 v[218:219], off
	v_lshl_add_u64 v[218:219], s[40:41], 0, v[134:135]
	s_mov_b32 m0, s42
	s_nop 0
	global_load_lds_dwordx4 v[218:219], off
	v_lshl_add_u64 v[218:219], s[40:41], 0, v[130:131]
	s_add_i32 m0, s42, 0x2000
	s_nop 0
	global_load_lds_dwordx4 v[218:219], off
	v_lshl_add_u64 v[218:219], v[222:223], 0, s[8:9]
	s_mov_b32 m0, s80
	s_nop 0
	global_load_lds_dwordx4 v[218:219], off
	v_lshl_add_u64 v[218:219], v[224:225], 0, s[8:9]
	s_mov_b32 m0, s81
	s_nop 0
	global_load_lds_dwordx4 v[218:219], off
	s_waitcnt vmcnt(8)
	s_waitcnt lgkmcnt(0)
	s_barrier
	s_setprio 1
	s_waitcnt lgkmcnt(0)
	v_mfma_f32_16x16x32_bf16 v[94:97], v[154:157], v[186:189], v[94:97]
	v_mfma_f32_16x16x32_bf16 v[90:93], v[162:165], v[186:189], v[90:93]
	v_mfma_f32_16x16x32_bf16 v[86:89], v[154:157], v[194:197], v[86:89]
	v_mfma_f32_16x16x32_bf16 v[82:85], v[162:165], v[194:197], v[82:85]
	v_mfma_f32_16x16x32_bf16 v[74:77], v[154:157], v[202:205], v[74:77]
	v_mfma_f32_16x16x32_bf16 v[66:69], v[162:165], v[202:205], v[66:69]
	v_mfma_f32_16x16x32_bf16 v[58:61], v[154:157], v[210:213], v[58:61]
	v_mfma_f32_16x16x32_bf16 v[50:53], v[162:165], v[210:213], v[50:53]
	v_mfma_f32_16x16x32_bf16 v[94:97], v[158:161], v[190:193], v[94:97]
	v_mfma_f32_16x16x32_bf16 v[90:93], v[166:169], v[190:193], v[90:93]
	v_mfma_f32_16x16x32_bf16 v[86:89], v[158:161], v[198:201], v[86:89]
	v_mfma_f32_16x16x32_bf16 v[82:85], v[166:169], v[198:201], v[82:85]
	v_mfma_f32_16x16x32_bf16 v[74:77], v[158:161], v[206:209], v[74:77]
	v_mfma_f32_16x16x32_bf16 v[66:69], v[166:169], v[206:209], v[66:69]
	v_mfma_f32_16x16x32_bf16 v[58:61], v[158:161], v[214:217], v[58:61]
	v_mfma_f32_16x16x32_bf16 v[50:53], v[166:169], v[214:217], v[50:53]
	s_setprio 0
	s_setprio 1
	v_mfma_f32_16x16x32_bf16 v[30:33], v[170:173], v[186:189], v[30:33]
	v_mfma_f32_16x16x32_bf16 v[26:29], v[178:181], v[186:189], v[26:29]
	v_mfma_f32_16x16x32_bf16 v[22:25], v[170:173], v[194:197], v[22:25]
	v_mfma_f32_16x16x32_bf16 v[18:21], v[178:181], v[194:197], v[18:21]
	v_mfma_f32_16x16x32_bf16 v[14:17], v[170:173], v[202:205], v[14:17]
	v_mfma_f32_16x16x32_bf16 v[10:13], v[178:181], v[202:205], v[10:13]
	v_mfma_f32_16x16x32_bf16 v[6:9], v[170:173], v[210:213], v[6:9]
	v_mfma_f32_16x16x32_bf16 v[2:5], v[178:181], v[210:213], v[2:5]
	v_mfma_f32_16x16x32_bf16 v[30:33], v[174:177], v[190:193], v[30:33]
	v_mfma_f32_16x16x32_bf16 v[26:29], v[182:185], v[190:193], v[26:29]
	v_mfma_f32_16x16x32_bf16 v[22:25], v[174:177], v[198:201], v[22:25]
	v_mfma_f32_16x16x32_bf16 v[18:21], v[182:185], v[198:201], v[18:21]
	v_mfma_f32_16x16x32_bf16 v[14:17], v[174:177], v[206:209], v[14:17]
	v_mfma_f32_16x16x32_bf16 v[10:13], v[182:185], v[206:209], v[10:13]
	v_mfma_f32_16x16x32_bf16 v[6:9], v[174:177], v[214:217], v[6:9]
	v_mfma_f32_16x16x32_bf16 v[2:5], v[182:185], v[214:217], v[2:5]
	s_setprio 0
	s_barrier
	s_add_i32 s89, s89, 2
	s_add_u32 s38, s38, 0x100
	s_addc_u32 s39, s39, 0
	s_add_u32 s87, s87, 0x100
	s_addc_u32 s88, s88, 0
	s_cmp_gt_u32 s89, 13
	s_cbranch_scc0 .LBB0_127
	s_and_b64 vcc, exec, s[10:11]
	s_cbranch_vccz .LBB0_130
	s_barrier
.LBB0_130:
	s_lshl_b32 s25, s37, 2
	s_lshr_b32 s94, s79, 5
	s_add_i32 s94, s25, s94
	s_mov_b32 s95, 0
	s_lshl_b64 s[94:95], s[94:95], 23
	s_and_b32 s25, s79, 32
	s_lshl_b32 s25, s25, 1
	s_sub_u32 s94, s94, s25
	s_subb_u32 s95, s95, 0
	v_lshl_add_u32 v154, s36, 8, v1
	v_lshlrev_b32_e32 v154, 7, v154
	v_mov_b32_e32 v155, 0
	v_lshl_add_u64 v[156:157], v[138:139], 0, s[94:95]
	v_lshl_add_u64 v[156:157], v[156:157], 0, v[154:155]
	v_and_b32_e32 v158, 1, v1
	v_lshlrev_b32_e32 v159, 6, v158
	v_sub_u32_e32 v160, 0, v159
	v_sub_u32_e32 v161, 0, v158
	v_sub_u32_e32 v162, 0x80, v159
	v_mov_b32_e32 v163, 0
	v_lshl_add_u64 v[164:165], v[156:157], 0, v[160:161]
	v_lshl_add_u64 v[166:167], v[156:157], 0, v[162:163]
	s_mov_b64 s[94:95], 0x1000
	s_mov_b64 s[96:97], 0x3000
	s_mov_b32 vcc_lo, 0x55555555
	s_mov_b32 vcc_hi, 0x55555555
	v_cvt_pk_bf16_f32 v168, v126, v127
	v_cvt_pk_bf16_f32 v169, v128, v129
	v_cvt_pk_bf16_f32 v170, v122, v123
	v_cvt_pk_bf16_f32 v171, v124, v125
	v_cvt_pk_bf16_f32 v172, v78, v79
	v_cvt_pk_bf16_f32 v173, v80, v81
	v_cvt_pk_bf16_f32 v174, v70, v71
	v_cvt_pk_bf16_f32 v175, v72, v73
	s_nop 1
	v_cndmask_b32_dpp v176, v172, v168, vcc quad_perm:[1,0,3,2] row_mask:0xf bank_mask:0xf
	v_cndmask_b32_dpp v177, v173, v169, vcc quad_perm:[1,0,3,2] row_mask:0xf bank_mask:0xf
	v_cndmask_b32_dpp v178, v174, v170, vcc quad_perm:[1,0,3,2] row_mask:0xf bank_mask:0xf
	v_cndmask_b32_dpp v179, v175, v171, vcc quad_perm:[1,0,3,2] row_mask:0xf bank_mask:0xf
	s_not_b64 vcc, vcc
	s_nop 0
	v_cndmask_b32_dpp v172, v168, v172, vcc quad_perm:[1,0,3,2] row_mask:0xf bank_mask:0xf
	v_cndmask_b32_dpp v173, v169, v173, vcc quad_perm:[1,0,3,2] row_mask:0xf bank_mask:0xf
	v_cndmask_b32_dpp v174, v170, v174, vcc quad_perm:[1,0,3,2] row_mask:0xf bank_mask:0xf
	v_cndmask_b32_dpp v175, v171, v175, vcc quad_perm:[1,0,3,2] row_mask:0xf bank_mask:0xf
	s_not_b64 vcc, vcc
	global_store_dwordx4 v[164:165], v[176:179], off nt
	global_store_dwordx4 v[166:167], v[172:175], off nt
	v_mov_b32_e32 v126, 0
	v_mov_b32_e32 v127, 0
	v_mov_b32_e32 v128, 0
	v_mov_b32_e32 v129, 0
	v_mov_b32_e32 v122, 0
	v_mov_b32_e32 v123, 0
	v_mov_b32_e32 v124, 0
	v_mov_b32_e32 v125, 0
	v_mov_b32_e32 v78, 0
	v_mov_b32_e32 v79, 0
	v_mov_b32_e32 v80, 0
	v_mov_b32_e32 v81, 0
	v_mov_b32_e32 v70, 0
	v_mov_b32_e32 v71, 0
	v_mov_b32_e32 v72, 0
	v_mov_b32_e32 v73, 0
	v_cvt_pk_bf16_f32 v180, v118, v119
	v_cvt_pk_bf16_f32 v181, v120, v121
	v_cvt_pk_bf16_f32 v182, v114, v115
	v_cvt_pk_bf16_f32 v183, v116, v117
	v_cvt_pk_bf16_f32 v184, v62, v63
	v_cvt_pk_bf16_f32 v185, v64, v65
	v_cvt_pk_bf16_f32 v186, v54, v55
	v_cvt_pk_bf16_f32 v187, v56, v57
	s_nop 1
	v_cndmask_b32_dpp v188, v184, v180, vcc quad_perm:[1,0,3,2] row_mask:0xf bank_mask:0xf
	v_cndmask_b32_dpp v189, v185, v181, vcc quad_perm:[1,0,3,2] row_mask:0xf bank_mask:0xf
	v_cndmask_b32_dpp v190, v186, v182, vcc quad_perm:[1,0,3,2] row_mask:0xf bank_mask:0xf
	v_cndmask_b32_dpp v191, v187, v183, vcc quad_perm:[1,0,3,2] row_mask:0xf bank_mask:0xf
	s_not_b64 vcc, vcc
	s_nop 0
	v_cndmask_b32_dpp v184, v180, v184, vcc quad_perm:[1,0,3,2] row_mask:0xf bank_mask:0xf
	v_cndmask_b32_dpp v185, v181, v185, vcc quad_perm:[1,0,3,2] row_mask:0xf bank_mask:0xf
	v_cndmask_b32_dpp v186, v182, v186, vcc quad_perm:[1,0,3,2] row_mask:0xf bank_mask:0xf
	v_cndmask_b32_dpp v187, v183, v187, vcc quad_perm:[1,0,3,2] row_mask:0xf bank_mask:0xf
	s_not_b64 vcc, vcc
	global_store_dwordx4 v[164:165], v[188:191], off offset:2048 nt
	global_store_dwordx4 v[166:167], v[184:187], off offset:2048 nt
	v_mov_b32_e32 v118, 0
	v_mov_b32_e32 v119, 0
	v_mov_b32_e32 v120, 0
	v_mov_b32_e32 v121, 0
	v_mov_b32_e32 v114, 0
	v_mov_b32_e32 v115, 0
	v_mov_b32_e32 v116, 0
	v_mov_b32_e32 v117, 0
	v_mov_b32_e32 v62, 0
	v_mov_b32_e32 v63, 0
	v_mov_b32_e32 v64, 0
	v_mov_b32_e32 v65, 0
	v_mov_b32_e32 v54, 0
	v_mov_b32_e32 v55, 0
	v_mov_b32_e32 v56, 0
	v_mov_b32_e32 v57, 0
	v_lshl_add_u64 v[164:165], v[164:165], 0, s[94:95]
	v_lshl_add_u64 v[166:167], v[166:167], 0, s[94:95]
	v_cvt_pk_bf16_f32 v168, v110, v111
	v_cvt_pk_bf16_f32 v169, v112, v113
	v_cvt_pk_bf16_f32 v170, v106, v107
	v_cvt_pk_bf16_f32 v171, v108, v109
	v_cvt_pk_bf16_f32 v172, v46, v47
	v_cvt_pk_bf16_f32 v173, v48, v49
	v_cvt_pk_bf16_f32 v174, v42, v43
	v_cvt_pk_bf16_f32 v175, v44, v45
	s_nop 1
	v_cndmask_b32_dpp v176, v172, v168, vcc quad_perm:[1,0,3,2] row_mask:0xf bank_mask:0xf
	v_cndmask_b32_dpp v177, v173, v169, vcc quad_perm:[1,0,3,2] row_mask:0xf bank_mask:0xf
	v_cndmask_b32_dpp v178, v174, v170, vcc quad_perm:[1,0,3,2] row_mask:0xf bank_mask:0xf
	v_cndmask_b32_dpp v179, v175, v171, vcc quad_perm:[1,0,3,2] row_mask:0xf bank_mask:0xf
	s_not_b64 vcc, vcc
	s_nop 0
	v_cndmask_b32_dpp v172, v168, v172, vcc quad_perm:[1,0,3,2] row_mask:0xf bank_mask:0xf
	v_cndmask_b32_dpp v173, v169, v173, vcc quad_perm:[1,0,3,2] row_mask:0xf bank_mask:0xf
	v_cndmask_b32_dpp v174, v170, v174, vcc quad_perm:[1,0,3,2] row_mask:0xf bank_mask:0xf
	v_cndmask_b32_dpp v175, v171, v175, vcc quad_perm:[1,0,3,2] row_mask:0xf bank_mask:0xf
	s_not_b64 vcc, vcc
	global_store_dwordx4 v[164:165], v[176:179], off nt
	global_store_dwordx4 v[166:167], v[172:175], off nt
	v_mov_b32_e32 v110, 0
	v_mov_b32_e32 v111, 0
	v_mov_b32_e32 v112, 0
	v_mov_b32_e32 v113, 0
	v_mov_b32_e32 v106, 0
	v_mov_b32_e32 v107, 0
	v_mov_b32_e32 v108, 0
	v_mov_b32_e32 v109, 0
	v_mov_b32_e32 v46, 0
	v_mov_b32_e32 v47, 0
	v_mov_b32_e32 v48, 0
	v_mov_b32_e32 v49, 0
	v_mov_b32_e32 v42, 0
	v_mov_b32_e32 v43, 0
	v_mov_b32_e32 v44, 0
	v_mov_b32_e32 v45, 0
	v_cvt_pk_bf16_f32 v180, v102, v103
	v_cvt_pk_bf16_f32 v181, v104, v105
	v_cvt_pk_bf16_f32 v182, v98, v99
	v_cvt_pk_bf16_f32 v183, v100, v101
	v_cvt_pk_bf16_f32 v184, v38, v39
	v_cvt_pk_bf16_f32 v185, v40, v41
	v_cvt_pk_bf16_f32 v186, v34, v35
	v_cvt_pk_bf16_f32 v187, v36, v37
	s_nop 1
	v_cndmask_b32_dpp v188, v184, v180, vcc quad_perm:[1,0,3,2] row_mask:0xf bank_mask:0xf
	v_cndmask_b32_dpp v189, v185, v181, vcc quad_perm:[1,0,3,2] row_mask:0xf bank_mask:0xf
	v_cndmask_b32_dpp v190, v186, v182, vcc quad_perm:[1,0,3,2] row_mask:0xf bank_mask:0xf
	v_cndmask_b32_dpp v191, v187, v183, vcc quad_perm:[1,0,3,2] row_mask:0xf bank_mask:0xf
	s_not_b64 vcc, vcc
	s_nop 0
	v_cndmask_b32_dpp v184, v180, v184, vcc quad_perm:[1,0,3,2] row_mask:0xf bank_mask:0xf
	v_cndmask_b32_dpp v185, v181, v185, vcc quad_perm:[1,0,3,2] row_mask:0xf bank_mask:0xf
	v_cndmask_b32_dpp v186, v182, v186, vcc quad_perm:[1,0,3,2] row_mask:0xf bank_mask:0xf
	v_cndmask_b32_dpp v187, v183, v187, vcc quad_perm:[1,0,3,2] row_mask:0xf bank_mask:0xf
	s_not_b64 vcc, vcc
	global_store_dwordx4 v[164:165], v[188:191], off offset:2048 nt
	global_store_dwordx4 v[166:167], v[184:187], off offset:2048 nt
	v_mov_b32_e32 v102, 0
	v_mov_b32_e32 v103, 0
	v_mov_b32_e32 v104, 0
	v_mov_b32_e32 v105, 0
	v_mov_b32_e32 v98, 0
	v_mov_b32_e32 v99, 0
	v_mov_b32_e32 v100, 0
	v_mov_b32_e32 v101, 0
	v_mov_b32_e32 v38, 0
	v_mov_b32_e32 v39, 0
	v_mov_b32_e32 v40, 0
	v_mov_b32_e32 v41, 0
	v_mov_b32_e32 v34, 0
	v_mov_b32_e32 v35, 0
	v_mov_b32_e32 v36, 0
	v_mov_b32_e32 v37, 0
	v_lshl_add_u64 v[164:165], v[164:165], 0, s[96:97]
	v_lshl_add_u64 v[166:167], v[166:167], 0, s[96:97]
	v_cvt_pk_bf16_f32 v168, v94, v95
	v_cvt_pk_bf16_f32 v169, v96, v97
	v_cvt_pk_bf16_f32 v170, v90, v91
	v_cvt_pk_bf16_f32 v171, v92, v93
	v_cvt_pk_bf16_f32 v172, v30, v31
	v_cvt_pk_bf16_f32 v173, v32, v33
	v_cvt_pk_bf16_f32 v174, v26, v27
	v_cvt_pk_bf16_f32 v175, v28, v29
	s_nop 1
	v_cndmask_b32_dpp v176, v172, v168, vcc quad_perm:[1,0,3,2] row_mask:0xf bank_mask:0xf
	v_cndmask_b32_dpp v177, v173, v169, vcc quad_perm:[1,0,3,2] row_mask:0xf bank_mask:0xf
	v_cndmask_b32_dpp v178, v174, v170, vcc quad_perm:[1,0,3,2] row_mask:0xf bank_mask:0xf
	v_cndmask_b32_dpp v179, v175, v171, vcc quad_perm:[1,0,3,2] row_mask:0xf bank_mask:0xf
	s_not_b64 vcc, vcc
	s_nop 0
	v_cndmask_b32_dpp v172, v168, v172, vcc quad_perm:[1,0,3,2] row_mask:0xf bank_mask:0xf
	v_cndmask_b32_dpp v173, v169, v173, vcc quad_perm:[1,0,3,2] row_mask:0xf bank_mask:0xf
	v_cndmask_b32_dpp v174, v170, v174, vcc quad_perm:[1,0,3,2] row_mask:0xf bank_mask:0xf
	v_cndmask_b32_dpp v175, v171, v175, vcc quad_perm:[1,0,3,2] row_mask:0xf bank_mask:0xf
	s_not_b64 vcc, vcc
	global_store_dwordx4 v[164:165], v[176:179], off nt
	global_store_dwordx4 v[166:167], v[172:175], off nt
	v_mov_b32_e32 v94, 0
	v_mov_b32_e32 v95, 0
	v_mov_b32_e32 v96, 0
	v_mov_b32_e32 v97, 0
	v_mov_b32_e32 v90, 0
	v_mov_b32_e32 v91, 0
	v_mov_b32_e32 v92, 0
	v_mov_b32_e32 v93, 0
	v_mov_b32_e32 v30, 0
	v_mov_b32_e32 v31, 0
	v_mov_b32_e32 v32, 0
	v_mov_b32_e32 v33, 0
	v_mov_b32_e32 v26, 0
	v_mov_b32_e32 v27, 0
	v_mov_b32_e32 v28, 0
	v_mov_b32_e32 v29, 0
	v_cvt_pk_bf16_f32 v180, v86, v87
	v_cvt_pk_bf16_f32 v181, v88, v89
	v_cvt_pk_bf16_f32 v182, v82, v83
	v_cvt_pk_bf16_f32 v183, v84, v85
	v_cvt_pk_bf16_f32 v184, v22, v23
	v_cvt_pk_bf16_f32 v185, v24, v25
	v_cvt_pk_bf16_f32 v186, v18, v19
	v_cvt_pk_bf16_f32 v187, v20, v21
	s_nop 1
	v_cndmask_b32_dpp v188, v184, v180, vcc quad_perm:[1,0,3,2] row_mask:0xf bank_mask:0xf
	v_cndmask_b32_dpp v189, v185, v181, vcc quad_perm:[1,0,3,2] row_mask:0xf bank_mask:0xf
	v_cndmask_b32_dpp v190, v186, v182, vcc quad_perm:[1,0,3,2] row_mask:0xf bank_mask:0xf
	v_cndmask_b32_dpp v191, v187, v183, vcc quad_perm:[1,0,3,2] row_mask:0xf bank_mask:0xf
	s_not_b64 vcc, vcc
	s_nop 0
	v_cndmask_b32_dpp v184, v180, v184, vcc quad_perm:[1,0,3,2] row_mask:0xf bank_mask:0xf
	v_cndmask_b32_dpp v185, v181, v185, vcc quad_perm:[1,0,3,2] row_mask:0xf bank_mask:0xf
	v_cndmask_b32_dpp v186, v182, v186, vcc quad_perm:[1,0,3,2] row_mask:0xf bank_mask:0xf
	v_cndmask_b32_dpp v187, v183, v187, vcc quad_perm:[1,0,3,2] row_mask:0xf bank_mask:0xf
	s_not_b64 vcc, vcc
	global_store_dwordx4 v[164:165], v[188:191], off offset:2048 nt
	global_store_dwordx4 v[166:167], v[184:187], off offset:2048 nt
	v_mov_b32_e32 v86, 0
	v_mov_b32_e32 v87, 0
	v_mov_b32_e32 v88, 0
	v_mov_b32_e32 v89, 0
	v_mov_b32_e32 v82, 0
	v_mov_b32_e32 v83, 0
	v_mov_b32_e32 v84, 0
	v_mov_b32_e32 v85, 0
	v_mov_b32_e32 v22, 0
	v_mov_b32_e32 v23, 0
	v_mov_b32_e32 v24, 0
	v_mov_b32_e32 v25, 0
	v_mov_b32_e32 v18, 0
	v_mov_b32_e32 v19, 0
	v_mov_b32_e32 v20, 0
	v_mov_b32_e32 v21, 0
	v_lshl_add_u64 v[164:165], v[164:165], 0, s[94:95]
	v_lshl_add_u64 v[166:167], v[166:167], 0, s[94:95]
	v_cvt_pk_bf16_f32 v168, v74, v75
	v_cvt_pk_bf16_f32 v169, v76, v77
	v_cvt_pk_bf16_f32 v170, v66, v67
	v_cvt_pk_bf16_f32 v171, v68, v69
	v_cvt_pk_bf16_f32 v172, v14, v15
	v_cvt_pk_bf16_f32 v173, v16, v17
	v_cvt_pk_bf16_f32 v174, v10, v11
	v_cvt_pk_bf16_f32 v175, v12, v13
	s_nop 1
	v_cndmask_b32_dpp v176, v172, v168, vcc quad_perm:[1,0,3,2] row_mask:0xf bank_mask:0xf
	v_cndmask_b32_dpp v177, v173, v169, vcc quad_perm:[1,0,3,2] row_mask:0xf bank_mask:0xf
	v_cndmask_b32_dpp v178, v174, v170, vcc quad_perm:[1,0,3,2] row_mask:0xf bank_mask:0xf
	v_cndmask_b32_dpp v179, v175, v171, vcc quad_perm:[1,0,3,2] row_mask:0xf bank_mask:0xf
	s_not_b64 vcc, vcc
	s_nop 0
	v_cndmask_b32_dpp v172, v168, v172, vcc quad_perm:[1,0,3,2] row_mask:0xf bank_mask:0xf
	v_cndmask_b32_dpp v173, v169, v173, vcc quad_perm:[1,0,3,2] row_mask:0xf bank_mask:0xf
	v_cndmask_b32_dpp v174, v170, v174, vcc quad_perm:[1,0,3,2] row_mask:0xf bank_mask:0xf
	v_cndmask_b32_dpp v175, v171, v175, vcc quad_perm:[1,0,3,2] row_mask:0xf bank_mask:0xf
	s_not_b64 vcc, vcc
	global_store_dwordx4 v[164:165], v[176:179], off nt
	global_store_dwordx4 v[166:167], v[172:175], off nt
	v_mov_b32_e32 v74, 0
	v_mov_b32_e32 v75, 0
	v_mov_b32_e32 v76, 0
	v_mov_b32_e32 v77, 0
	v_mov_b32_e32 v66, 0
	v_mov_b32_e32 v67, 0
	v_mov_b32_e32 v68, 0
	v_mov_b32_e32 v69, 0
	v_mov_b32_e32 v14, 0
	v_mov_b32_e32 v15, 0
	v_mov_b32_e32 v16, 0
	v_mov_b32_e32 v17, 0
	v_mov_b32_e32 v10, 0
	v_mov_b32_e32 v11, 0
	v_mov_b32_e32 v12, 0
	v_mov_b32_e32 v13, 0
	v_cvt_pk_bf16_f32 v180, v58, v59
	v_cvt_pk_bf16_f32 v181, v60, v61
	v_cvt_pk_bf16_f32 v182, v50, v51
	v_cvt_pk_bf16_f32 v183, v52, v53
	v_cvt_pk_bf16_f32 v184, v6, v7
	v_cvt_pk_bf16_f32 v185, v8, v9
	v_cvt_pk_bf16_f32 v186, v2, v3
	v_cvt_pk_bf16_f32 v187, v4, v5
	s_nop 1
	v_cndmask_b32_dpp v188, v184, v180, vcc quad_perm:[1,0,3,2] row_mask:0xf bank_mask:0xf
	v_cndmask_b32_dpp v189, v185, v181, vcc quad_perm:[1,0,3,2] row_mask:0xf bank_mask:0xf
	v_cndmask_b32_dpp v190, v186, v182, vcc quad_perm:[1,0,3,2] row_mask:0xf bank_mask:0xf
	v_cndmask_b32_dpp v191, v187, v183, vcc quad_perm:[1,0,3,2] row_mask:0xf bank_mask:0xf
	s_not_b64 vcc, vcc
	s_nop 0
	v_cndmask_b32_dpp v184, v180, v184, vcc quad_perm:[1,0,3,2] row_mask:0xf bank_mask:0xf
	v_cndmask_b32_dpp v185, v181, v185, vcc quad_perm:[1,0,3,2] row_mask:0xf bank_mask:0xf
	v_cndmask_b32_dpp v186, v182, v186, vcc quad_perm:[1,0,3,2] row_mask:0xf bank_mask:0xf
	v_cndmask_b32_dpp v187, v183, v187, vcc quad_perm:[1,0,3,2] row_mask:0xf bank_mask:0xf
	s_not_b64 vcc, vcc
	global_store_dwordx4 v[164:165], v[188:191], off offset:2048 nt
	global_store_dwordx4 v[166:167], v[184:187], off offset:2048 nt
	v_mov_b32_e32 v58, 0
	v_mov_b32_e32 v59, 0
	v_mov_b32_e32 v60, 0
	v_mov_b32_e32 v61, 0
	v_mov_b32_e32 v50, 0
	v_mov_b32_e32 v51, 0
	v_mov_b32_e32 v52, 0
	v_mov_b32_e32 v53, 0
	v_mov_b32_e32 v6, 0
	v_mov_b32_e32 v7, 0
	v_mov_b32_e32 v8, 0
	v_mov_b32_e32 v9, 0
	v_mov_b32_e32 v2, 0
	v_mov_b32_e32 v3, 0
	v_mov_b32_e32 v4, 0
	v_mov_b32_e32 v5, 0
	s_mov_b32 s98, 1
	s_andn2_b64 vcc, exec, s[0:1]
	s_mov_b64 s[0:1], -1
	s_cbranch_vccnz .LBB0_123
	s_andn2_b64 vcc, exec, s[6:7]
	s_cbranch_vccnz .LBB0_122
	s_barrier
	s_branch .LBB0_122

.LBB0_233:
	ds_read_b128 v[176:179], v120
	ds_read_b128 v[180:183], v120 offset:16
	ds_read_b64_tr_b16 v[134:135], v117 offset:576
	ds_read_b64_tr_b16 v[132:133], v117
	ds_read_b128 v[136:139], v125 offset:18432
	ds_read_b64_tr_b16 v[142:143], v117 offset:608
	ds_read_b64_tr_b16 v[140:141], v117 offset:32
	ds_read_b128 v[144:147], v125 offset:18496
	ds_read_b64_tr_b16 v[150:151], v117 offset:4608
	ds_read_b64_tr_b16 v[152:153], v117 offset:5184
	ds_read_b64_tr_b16 v[156:157], v117 offset:5216
	ds_read_b64_tr_b16 v[154:155], v117 offset:4640
	s_waitcnt lgkmcnt(7)
	v_mfma_f32_16x16x32_bf16 v[50:53], v[132:135], v[136:139], v[50:53]
	v_exp_f32_e64 v184, -v176
	v_exp_f32_e64 v185, -v177
	ds_read_b64_tr_b16 v[158:159], v101 offset:55296
	ds_read_b64_tr_b16 v[160:161], v101 offset:55872
	v_add_u32_e32 v131, v94, v97
	s_waitcnt lgkmcnt(7)
	v_mfma_f32_16x16x32_bf16 v[136:139], v[140:143], v[136:139], v[54:57]
	v_exp_f32_e32 v192, v176
	v_exp_f32_e32 v193, v177
	s_waitcnt lgkmcnt(4)
	v_mfma_f32_16x16x32_bf16 v[50:53], v[150:153], v[144:147], v[50:53]
	v_exp_f32_e64 v186, -v178
	v_exp_f32_e64 v187, -v179
	s_nop 0
	v_add_u32_e32 v56, s29, v71
	v_add_u32_e32 v54, 64, v129
	v_cndmask_b32_e64 v54, v54, v56, s[0:1]
	s_waitcnt lgkmcnt(2)
	v_mfma_f32_16x16x32_bf16 v[136:139], v[154:157], v[144:147], v[136:139]
	v_exp_f32_e32 v194, v178
	v_exp_f32_e32 v195, v179
	ds_read_b64_tr_b16 v[144:145], v101 offset:59904
	ds_read_b64_tr_b16 v[146:147], v101 offset:60480
	v_add_u32_e32 v54, s30, v54
	v_ashrrev_i32_e32 v55, 31, v54
	s_waitcnt lgkmcnt(2)
	v_mfma_f32_16x16x32_bf16 v[46:49], v[158:161], v[132:135], v[46:49]
	v_exp_f32_e64 v188, -v180
	v_exp_f32_e64 v189, -v181
	v_cvt_pk_bf16_f32 v172, v50, v51
	v_cvt_pk_bf16_f32 v173, v52, v53
	ds_read_b128 v[50:53], v118 offset:46080
	v_mfma_f32_16x16x32_bf16 v[42:45], v[158:161], v[140:143], v[42:45]
	v_exp_f32_e32 v196, v180
	v_exp_f32_e32 v197, v181
	v_lshlrev_b64 v[54:55], 10, v[54:55]
	v_lshl_add_u64 v[54:55], v[80:81], 0, v[54:55]
	s_nop 0
	s_waitcnt lgkmcnt(1)
	v_mfma_f32_16x16x32_bf16 v[46:49], v[144:147], v[150:153], v[46:49]
	v_exp_f32_e64 v190, -v182
	v_exp_f32_e64 v191, -v183
	v_cvt_pk_bf16_f32 v174, v136, v137
	v_cvt_pk_bf16_f32 v175, v138, v139
	s_nop 1
	v_permlane16_swap_b32_e32 v172, v174
	v_permlane16_swap_b32_e32 v173, v175
	global_store_dwordx4 v[54:55], v[172:175], off
	v_mfma_f32_16x16x32_bf16 v[42:45], v[144:147], v[154:157], v[42:45]
	v_exp_f32_e32 v198, v182
	v_exp_f32_e32 v199, v183
	s_nop 2
	s_waitcnt lgkmcnt(0)
	s_nop 0
	v_pk_mul_f32 v[48:49], v[52:53], v[48:49]
	v_pk_mul_f32 v[46:47], v[50:51], v[46:47]
	v_pk_mul_f32 v[44:45], v[52:53], v[44:45]
	v_pk_mul_f32 v[42:43], v[50:51], v[42:43]
	v_cvt_pk_bf16_f32 v50, v46, v47
	v_cvt_pk_bf16_f32 v51, v48, v49
	ds_write_b64 v131, v[50:51] offset:27648
	v_cvt_pk_bf16_f32 v50, v42, v43
	v_cvt_pk_bf16_f32 v51, v44, v45
	ds_write_b64 v119, v[50:51] offset:27648
	s_waitcnt vmcnt(8)
	v_lshlrev_b32_e32 v200, 16, v22
	v_and_b32_e32 v201, 0xffff0000, v22
	v_lshlrev_b32_e32 v202, 16, v23
	v_and_b32_e32 v203, 0xffff0000, v23
	v_lshlrev_b32_e32 v204, 16, v24
	v_and_b32_e32 v205, 0xffff0000, v24
	v_lshlrev_b32_e32 v206, 16, v25
	v_and_b32_e32 v207, 0xffff0000, v25
	v_pk_mul_f32 v[200:201], v[184:185], v[200:201]
	v_pk_mul_f32 v[202:203], v[186:187], v[202:203]
	v_pk_mul_f32 v[204:205], v[188:189], v[204:205]
	v_pk_mul_f32 v[206:207], v[190:191], v[206:207]
	v_cvt_pk_bf16_f32 v136, v200, v201
	v_cvt_pk_bf16_f32 v137, v202, v203
	v_cvt_pk_bf16_f32 v138, v204, v205
	v_cvt_pk_bf16_f32 v139, v206, v207
	s_waitcnt vmcnt(6)
	v_lshlrev_b32_e32 v200, 16, v18
	v_and_b32_e32 v201, 0xffff0000, v18
	v_lshlrev_b32_e32 v202, 16, v19
	v_and_b32_e32 v203, 0xffff0000, v19
	v_lshlrev_b32_e32 v204, 16, v20
	v_and_b32_e32 v205, 0xffff0000, v20
	v_lshlrev_b32_e32 v206, 16, v21
	v_and_b32_e32 v207, 0xffff0000, v21
	v_pk_mul_f32 v[200:201], v[192:193], v[200:201]
	v_pk_mul_f32 v[202:203], v[194:195], v[202:203]
	v_pk_mul_f32 v[204:205], v[196:197], v[204:205]
	v_pk_mul_f32 v[206:207], v[198:199], v[206:207]
	v_cvt_pk_bf16_f32 v18, v200, v201
	v_cvt_pk_bf16_f32 v19, v202, v203
	v_cvt_pk_bf16_f32 v20, v204, v205
	v_cvt_pk_bf16_f32 v21, v206, v207
	ds_write_b128 v111, v[18:21]
	ds_write_b128 v111, v[136:139] offset:64512
	s_and_saveexec_b64 s[26:27], vcc
	s_cbranch_execz .LBB0_235
	ds_write_b128 v126, v[192:195] offset:46336
	ds_write_b128 v126, v[196:199] offset:46352
.LBB0_235:
	s_or_b64 exec, exec, s[26:27]
	ds_write_b128 v121, v[10:13]
	s_waitcnt vmcnt(5)
	ds_write_b128 v111, v[14:17] offset:36864
	v_add_u32_e32 v10, s29, v90
	v_cndmask_b32_e64 v10, v130, v10, s[0:1]
	v_ashrrev_i32_e32 v11, 31, v10
	s_add_i32 s31, s31, 2
	v_lshlrev_b64 v[10:11], 7, v[10:11]
	s_min_u32 s26, s31, 60
	v_lshl_add_u64 v[12:13], v[72:73], 0, v[10:11]
	v_lshl_add_u64 v[14:15], v[76:77], 0, v[10:11]
	global_load_dwordx4 v[18:21], v[12:13], off
	global_load_dwordx4 v[22:25], v[14:15], off
	v_lshl_add_u32 v12, s26, 6, v90
	v_sub_u32_e32 v13, 0xfff, v12
	v_cndmask_b32_e64 v12, v13, v12, s[0:1]
	v_ashrrev_i32_e32 v13, 31, v12
	v_lshlrev_b64 v[54:55], 7, v[12:13]
	v_lshl_add_u64 v[10:11], v[78:79], 0, v[10:11]
	v_lshl_add_u64 v[14:15], v[74:75], 0, v[54:55]
	global_load_dwordx4 v[10:13], v[10:11], off
	s_nop 0
	global_load_dwordx4 v[14:17], v[14:15], off
	s_waitcnt lgkmcnt(0)
	s_barrier
	ds_read_b128 v[50:53], v95 offset:64512
	ds_read_b128 v[132:135], v125
	ds_read_b128 v[136:139], v125 offset:64
	ds_read_b128 v[140:143], v95 offset:64576
	ds_read_b128 v[144:147], v102 offset:2304
	ds_read_b128 v[150:153], v102 offset:2368
	s_waitcnt lgkmcnt(4)
	v_mfma_f32_16x16x32_bf16 v[50:53], v[50:53], v[132:135], 0
	ds_read_b128 v[154:157], v95 offset:27648
	ds_read_b128 v[158:161], v95 offset:27712
	ds_read_b128 v[162:165], v95 offset:29952
	ds_read_b128 v[166:169], v95 offset:30016
	s_waitcnt lgkmcnt(5)
	v_mfma_f32_16x16x32_bf16 v[144:147], v[144:147], v[132:135], 0
	v_mfma_f32_16x16x32_bf16 v[50:53], v[140:143], v[136:139], v[50:53]
	s_waitcnt lgkmcnt(4)
	v_mfma_f32_16x16x32_bf16 v[140:143], v[150:153], v[136:139], v[144:147]
	s_waitcnt lgkmcnt(3)
	v_mfma_f32_16x16x32_bf16 v[154:157], v[154:157], v[132:135], 0
	s_nop 3
	v_mul_f32_e64 v52, v60, v52
	v_mul_f32_e64 v53, v61, v53
	v_pk_mul_f32 v[50:51], v[58:59], v[50:51]
	v_pk_mul_f32 v[142:143], v[64:65], v[142:143]
	s_waitcnt lgkmcnt(1)
	v_mfma_f32_16x16x32_bf16 v[132:135], v[162:165], v[132:135], 0
	v_mul_f32_e64 v140, v62, v140
	v_mul_f32_e64 v141, v63, v141
	v_cvt_pk_bf16_f32 v50, v50, v51
	v_cvt_pk_bf16_f32 v51, v52, v53
	ds_write_b64 v115, v[50:51] offset:18432
	v_cvt_pk_bf16_f32 v50, v140, v141
	v_cvt_pk_bf16_f32 v51, v142, v143
	ds_write_b64 v116, v[50:51] offset:18432
	ds_read_b64_tr_b16 v[52:53], v112 offset:37440
	ds_read_b64_tr_b16 v[50:51], v112 offset:36864
	v_mfma_f32_16x16x32_bf16 v[144:147], v[158:161], v[136:139], v[154:157]
	s_waitcnt lgkmcnt(4)
	v_mfma_f32_16x16x32_bf16 v[132:135], v[166:169], v[136:139], v[132:135]
	ds_read_b64_tr_b16 v[138:139], v112 offset:37472
	ds_read_b64_tr_b16 v[136:137], v112 offset:36896
	ds_read_b64_tr_b16 v[140:141], v112 offset:41472
	ds_read_b64_tr_b16 v[142:143], v112 offset:42048
	ds_read_b64_tr_b16 v[152:153], v112 offset:42080
	ds_read_b64_tr_b16 v[150:151], v112 offset:41504
	s_waitcnt lgkmcnt(6)
	v_mfma_f32_16x16x32_bf16 v[50:53], v[50:53], v[2:5], 0
	s_waitcnt lgkmcnt(4)
	v_mfma_f32_16x16x32_bf16 v[136:139], v[136:139], v[2:5], 0
	s_waitcnt lgkmcnt(2)
	v_mfma_f32_16x16x32_bf16 v[50:53], v[140:143], v[6:9], v[50:53]
	s_waitcnt lgkmcnt(0)
	v_mfma_f32_16x16x32_bf16 v[136:139], v[150:153], v[6:9], v[136:139]
	s_nop 5
	ds_write_b128 v123, v[50:53]
	s_nop 0
	ds_write_b128 v124, v[136:139]
	s_waitcnt lgkmcnt(0)
	s_barrier
	ds_read_b128 v[176:179], v113
	ds_read_b128 v[180:183], v113 offset:16
	ds_read_b64_tr_b16 v[50:51], v122
	ds_read_b64_tr_b16 v[52:53], v122 offset:576
	ds_read_b64_tr_b16 v[138:139], v122 offset:608
	ds_read_b64_tr_b16 v[140:141], v122 offset:4608
	ds_read_b64_tr_b16 v[136:137], v122 offset:32
	ds_read_b128 v[150:153], v125 offset:18432
	ds_read_b128 v[154:157], v125 offset:18496
	ds_read_b128 v[158:161], v118 offset:46336
	ds_read_b64_tr_b16 v[142:143], v122 offset:5184
	s_waitcnt lgkmcnt(3)
	v_mfma_f32_16x16x32_bf16 v[144:147], v[50:53], v[150:153], v[144:147]
	v_exp_f32_e64 v184, -v176
	v_exp_f32_e64 v185, -v177
	v_mfma_f32_16x16x32_bf16 v[132:135], v[136:139], v[150:153], v[132:135]
	v_exp_f32_e32 v192, v176
	v_exp_f32_e32 v193, v177
	ds_read_b64_tr_b16 v[152:153], v122 offset:5216
	ds_read_b64_tr_b16 v[150:151], v122 offset:4640
	s_waitcnt lgkmcnt(2)
	v_mfma_f32_16x16x32_bf16 v[144:147], v[140:143], v[154:157], v[144:147]
	v_exp_f32_e64 v186, -v178
	v_exp_f32_e64 v187, -v179
	s_waitcnt lgkmcnt(0)
	v_mfma_f32_16x16x32_bf16 v[132:135], v[150:153], v[154:157], v[132:135]
	v_exp_f32_e32 v194, v178
	v_exp_f32_e32 v195, v179
	ds_read_b64_tr_b16 v[154:155], v101 offset:64512
	ds_read_b64_tr_b16 v[156:157], v101 offset:65088
	ds_read_b64_tr_b16 v[162:163], v105 offset:4608
	ds_read_b64_tr_b16 v[164:165], v105 offset:5184
	s_waitcnt lgkmcnt(2)
	v_mfma_f32_16x16x32_bf16 v[46:49], v[154:157], v[50:53], v[46:49]
	v_exp_f32_e64 v188, -v180
	v_exp_f32_e64 v189, -v181
	v_add_u32_e32 v50, 64, v56
	v_cndmask_b32_e64 v50, v129, v50, s[0:1]
	v_add_u32_e32 v50, s30, v50
	v_mfma_f32_16x16x32_bf16 v[42:45], v[154:157], v[136:139], v[42:45]
	v_exp_f32_e32 v196, v180
	v_exp_f32_e32 v197, v181
	v_ashrrev_i32_e32 v51, 31, v50
	v_lshlrev_b64 v[50:51], 10, v[50:51]
	v_lshl_add_u64 v[56:57], v[80:81], 0, v[50:51]
	s_waitcnt lgkmcnt(0)
	v_mfma_f32_16x16x32_bf16 v[46:49], v[162:165], v[140:143], v[46:49]
	v_exp_f32_e64 v190, -v182
	v_exp_f32_e64 v191, -v183
	v_cvt_pk_bf16_f32 v172, v144, v145
	v_cvt_pk_bf16_f32 v173, v146, v147
	s_nop 0
	v_mfma_f32_16x16x32_bf16 v[42:45], v[162:165], v[150:153], v[42:45]
	v_exp_f32_e32 v198, v182
	v_exp_f32_e32 v199, v183
	s_nop 2
	v_cvt_pk_bf16_f32 v174, v132, v133
	s_nop 2
	v_pk_mul_f32 v[48:49], v[160:161], v[48:49]
	v_pk_mul_f32 v[46:47], v[158:159], v[46:47]
	v_cvt_pk_bf16_f32 v51, v48, v49
	v_cvt_pk_bf16_f32 v50, v46, v47
	v_pk_mul_f32 v[44:45], v[160:161], v[44:45]
	v_pk_mul_f32 v[42:43], v[158:159], v[42:43]
	ds_write_b64 v131, v[50:51] offset:27648
	v_cvt_pk_bf16_f32 v50, v42, v43
	v_cvt_pk_bf16_f32 v51, v44, v45
	ds_write_b64 v119, v[50:51] offset:27648
	v_cvt_pk_bf16_f32 v175, v134, v135
	s_nop 1
	v_permlane16_swap_b32_e32 v172, v174
	v_permlane16_swap_b32_e32 v173, v175
	global_store_dwordx4 v[56:57], v[172:175], off
	s_waitcnt vmcnt(8)
	v_lshlrev_b32_e32 v200, 16, v38
	v_and_b32_e32 v201, 0xffff0000, v38
	v_lshlrev_b32_e32 v202, 16, v39
	v_and_b32_e32 v203, 0xffff0000, v39
	v_lshlrev_b32_e32 v204, 16, v40
	v_and_b32_e32 v205, 0xffff0000, v40
	v_lshlrev_b32_e32 v206, 16, v41
	v_and_b32_e32 v207, 0xffff0000, v41
	v_pk_mul_f32 v[200:201], v[184:185], v[200:201]
	v_pk_mul_f32 v[202:203], v[186:187], v[202:203]
	v_pk_mul_f32 v[204:205], v[188:189], v[204:205]
	v_pk_mul_f32 v[206:207], v[190:191], v[206:207]
	v_cvt_pk_bf16_f32 v136, v200, v201
	v_cvt_pk_bf16_f32 v137, v202, v203
	v_cvt_pk_bf16_f32 v138, v204, v205
	v_cvt_pk_bf16_f32 v139, v206, v207
	v_lshlrev_b32_e32 v200, 16, v34
	v_and_b32_e32 v201, 0xffff0000, v34
	v_lshlrev_b32_e32 v202, 16, v35
	v_and_b32_e32 v203, 0xffff0000, v35
	v_lshlrev_b32_e32 v204, 16, v36
	v_and_b32_e32 v205, 0xffff0000, v36
	v_lshlrev_b32_e32 v206, 16, v37
	v_and_b32_e32 v207, 0xffff0000, v37
	v_pk_mul_f32 v[200:201], v[192:193], v[200:201]
	v_pk_mul_f32 v[202:203], v[194:195], v[202:203]
	v_pk_mul_f32 v[204:205], v[196:197], v[204:205]
	v_pk_mul_f32 v[206:207], v[198:199], v[206:207]
	v_cvt_pk_bf16_f32 v34, v200, v201
	v_cvt_pk_bf16_f32 v35, v202, v203
	v_cvt_pk_bf16_f32 v36, v204, v205
	v_cvt_pk_bf16_f32 v37, v206, v207
	ds_write_b128 v111, v[34:37]
	ds_write_b128 v111, v[136:139] offset:55296
	s_and_saveexec_b64 s[26:27], vcc
	s_cbranch_execz .LBB0_232
	ds_write_b128 v126, v[192:195] offset:46080
	ds_write_b128 v126, v[196:199] offset:46096
	s_branch .LBB0_232

.LBB0_308:
	s_and_b32 s20, s11, 1
	s_lshl_b32 s0, s20, 2
	s_add_i32 s0, s8, s0
	s_lshl_b64 s[6:7], s[0:1], 23
	s_and_b32 s0, s10, 0xfffff000
	s_lshr_b32 s21, s11, 1
	s_waitcnt lgkmcnt(0)
	s_barrier
	s_waitcnt vmcnt(4)
	ds_write_b128 v92, v[14:17]
	ds_write_b128 v92, v[30:33] offset:33792
	ds_write_b128 v92, v[10:13] offset:16
	ds_write_b128 v92, v[26:29] offset:33808
	ds_write_b128 v92, v[6:9] offset:32
	ds_write_b128 v92, v[22:25] offset:33824
	ds_write_b128 v92, v[2:5] offset:48
	ds_write_b128 v92, v[18:21] offset:33840
	v_or_b32_e32 v2, s0, v90
	v_and_or_b32 v82, s21, 63, v2
	v_ashrrev_i32_e32 v83, 31, v82
	v_lshl_add_u64 v[2:3], v[76:77], 0, s[6:7]
	v_lshlrev_b64 v[4:5], 7, v[82:83]
	v_lshl_add_u64 v[4:5], v[2:3], 0, v[4:5]
	s_waitcnt lgkmcnt(0)
	s_barrier
	v_mov_b32_e32 v70, v120
	v_mov_b32_e32 v71, v121
	v_mov_b32_e32 v72, v122
	v_mov_b32_e32 v73, v123
	v_mov_b32_e32 v58, v124
	v_mov_b32_e32 v59, v125
	v_mov_b32_e32 v60, v126
	v_mov_b32_e32 v61, v127
	v_mov_b32_e32 v42, v128
	v_mov_b32_e32 v43, v129
	v_mov_b32_e32 v44, v130
	v_mov_b32_e32 v45, v131
	v_mov_b32_e32 v34, v132
	v_mov_b32_e32 v35, v133
	v_mov_b32_e32 v36, v134
	v_mov_b32_e32 v37, v135
	v_or_b32_e32 v84, 0x400, v82
	v_ashrrev_i32_e32 v85, 31, v84
	s_add_i32 s0, s11, s3
	v_lshlrev_b64 v[4:5], 7, v[84:85]
	v_or_b32_e32 v80, 0x800, v82
	s_cmpk_lt_i32 s0, 0x800
	v_lshl_add_u64 v[4:5], v[2:3], 0, v[4:5]
	v_ashrrev_i32_e32 v81, 31, v80
	s_cselect_b64 s[6:7], -1, 0
	v_lshlrev_b64 v[4:5], 7, v[80:81]
	v_or_b32_e32 v78, 0xc00, v82
	s_and_b64 s[22:23], s[6:7], exec
	v_lshl_add_u64 v[4:5], v[2:3], 0, v[4:5]
	v_ashrrev_i32_e32 v79, 31, v78
	s_cselect_b32 s11, s0, s11
	s_and_b32 s80, s11, 1
	s_lshl_b32 s80, s80, 2
	s_add_i32 s80, s8, s80
	s_mov_b32 s81, 0
	s_lshl_b64 s[80:81], s[80:81], 23
	s_lshl_b32 s82, s11, 5
	s_and_b32 s82, s82, 0xfffff000
	s_lshr_b32 s83, s11, 1
	s_and_b32 s83, s83, 63
	s_or_b32 s82, s82, s83
	v_or_b32_e32 v116, s82, v90
	v_lshlrev_b32_e32 v116, 7, v116
	v_mov_b32_e32 v117, 0
	v_lshl_add_u64 v[116:117], v[76:77], 0, v[116:117]
	v_lshl_add_u64 v[116:117], v[116:117], 0, s[80:81]
	global_load_dwordx4 v[120:123], v[116:117], off
	v_lshl_add_u64 v[116:117], v[116:117], 0, s[84:85]
	global_load_dwordx4 v[124:127], v[116:117], off
	v_lshl_add_u64 v[116:117], v[116:117], 0, s[84:85]
	global_load_dwordx4 v[128:131], v[116:117], off
	v_lshl_add_u64 v[116:117], v[116:117], 0, s[84:85]
	global_load_dwordx4 v[132:135], v[116:117], off
	v_lshlrev_b64 v[4:5], 7, v[78:79]
	s_lshl_b32 s21, s11, 5
	v_lshl_add_u64 v[2:3], v[2:3], 0, v[4:5]
	s_andn2_b32 s21, s21, 63
	v_or_b32_e32 v2, s21, v1
	v_ashrrev_i32_e32 v3, 31, v2
	s_lshl_b32 s11, s11, 8
	v_lshlrev_b64 v[2:3], 9, v[2:3]
	s_and_b32 s11, s11, 0x100
	v_or_b32_e32 v2, s11, v2
	v_or_b32_e32 v2, v2, v74
	v_lshlrev_b64 v[2:3], 1, v[2:3]
	v_lshl_add_u64 v[38:39], s[14:15], 0, v[2:3]
	v_lshl_add_u64 v[40:41], s[12:13], 0, v[2:3]
	global_load_dwordx4 v[2:5], v[38:39], off offset:48
	global_load_dwordx4 v[6:9], v[38:39], off offset:32
	global_load_dwordx4 v[10:13], v[38:39], off offset:16
	global_load_dwordx4 v[14:17], v[38:39], off
	global_load_dwordx4 v[18:21], v[40:41], off offset:48
	global_load_dwordx4 v[22:25], v[40:41], off offset:32
	global_load_dwordx4 v[26:29], v[40:41], off offset:16
	global_load_dwordx4 v[30:33], v[40:41], off
	ds_read_b64_tr_b16 v[40:41], v93 offset:2112
	ds_read_b64_tr_b16 v[38:39], v93
	ds_read_b64_tr_b16 v[46:47], v93 offset:8
	ds_read_b64_tr_b16 v[48:49], v93 offset:2120
	ds_read_b128 v[50:53], v94
	ds_read_b128 v[62:65], v94 offset:4352
	ds_read_b128 v[86:89], v94 offset:8704
	ds_read_b128 v[100:103], v94 offset:13056
	s_waitcnt lgkmcnt(3)
	v_mfma_f32_16x16x32_bf16 v[54:57], v[38:41], v[50:53], 0
	v_lshlrev_b64 v[82:83], 11, v[82:83]
	s_add_i32 s10, s10, s9
	s_mov_b32 s11, s0
	v_mfma_f32_16x16x32_bf16 v[50:53], v[46:49], v[50:53], 0
	v_lshlrev_b32_e32 v95, 16, v70
	s_waitcnt lgkmcnt(2)
	v_mfma_f32_16x16x32_bf16 v[66:69], v[38:41], v[62:65], 0
	v_and_b32_e32 v70, 0xffff0000, v70
	v_mfma_f32_16x16x32_bf16 v[62:65], v[46:49], v[62:65], 0
	s_waitcnt lgkmcnt(1)
	v_mfma_f32_16x16x32_bf16 v[96:99], v[38:41], v[86:89], 0
	v_mfma_f32_16x16x32_bf16 v[86:89], v[46:49], v[86:89], 0
	s_waitcnt lgkmcnt(0)
	v_mfma_f32_16x16x32_bf16 v[38:41], v[38:41], v[100:103], 0
	v_mfma_f32_16x16x32_bf16 v[46:49], v[46:49], v[100:103], 0
	ds_read_b64_tr_b16 v[100:101], v93 offset:16896
	ds_read_b64_tr_b16 v[102:103], v93 offset:19008
	ds_read_b64_tr_b16 v[104:105], v93 offset:16904
	ds_read_b64_tr_b16 v[106:107], v93 offset:19016
	ds_read_b128 v[108:111], v94 offset:64
	s_waitcnt lgkmcnt(0)
	v_mfma_f32_16x16x32_bf16 v[54:57], v[100:103], v[108:111], v[54:57]
	v_mfma_f32_16x16x32_bf16 v[50:53], v[104:107], v[108:111], v[50:53]
	ds_read_b128 v[108:111], v94 offset:4416
	s_waitcnt lgkmcnt(0)
	v_mfma_f32_16x16x32_bf16 v[66:69], v[100:103], v[108:111], v[66:69]
	v_mfma_f32_16x16x32_bf16 v[62:65], v[104:107], v[108:111], v[62:65]
	ds_read_b128 v[108:111], v94 offset:8768
	s_waitcnt lgkmcnt(0)
	v_mfma_f32_16x16x32_bf16 v[96:99], v[100:103], v[108:111], v[96:99]
	v_mfma_f32_16x16x32_bf16 v[86:89], v[104:107], v[108:111], v[86:89]
	ds_read_b128 v[108:111], v94 offset:13120
	s_waitcnt lgkmcnt(0)
	v_mfma_f32_16x16x32_bf16 v[38:41], v[100:103], v[108:111], v[38:41]
	v_mfma_f32_16x16x32_bf16 v[46:49], v[104:107], v[108:111], v[46:49]
	ds_read_b64_tr_b16 v[100:101], v93 offset:33792
	ds_read_b64_tr_b16 v[102:103], v93 offset:35904
	ds_read_b64_tr_b16 v[104:105], v93 offset:33800
	ds_read_b64_tr_b16 v[106:107], v93 offset:35912
	ds_read_b128 v[108:111], v94 offset:128
	s_waitcnt lgkmcnt(0)
	v_mfma_f32_16x16x32_bf16 v[54:57], v[100:103], v[108:111], v[54:57]
	v_mfma_f32_16x16x32_bf16 v[50:53], v[104:107], v[108:111], v[50:53]
	ds_read_b128 v[108:111], v94 offset:4480
	s_waitcnt lgkmcnt(0)
	v_mfma_f32_16x16x32_bf16 v[66:69], v[100:103], v[108:111], v[66:69]
	v_mfma_f32_16x16x32_bf16 v[62:65], v[104:107], v[108:111], v[62:65]
	ds_read_b128 v[108:111], v94 offset:8832
	s_waitcnt lgkmcnt(0)
	v_mfma_f32_16x16x32_bf16 v[96:99], v[100:103], v[108:111], v[96:99]
	v_mfma_f32_16x16x32_bf16 v[86:89], v[104:107], v[108:111], v[86:89]
	ds_read_b128 v[108:111], v94 offset:13184
	s_waitcnt lgkmcnt(0)
	v_mfma_f32_16x16x32_bf16 v[38:41], v[100:103], v[108:111], v[38:41]
	v_mfma_f32_16x16x32_bf16 v[100:103], v[104:107], v[108:111], v[46:49]
	s_nop 2
	ds_read_b64_tr_b16 v[46:47], v93 offset:50688
	ds_read_b64_tr_b16 v[48:49], v93 offset:52800
	ds_read_b64_tr_b16 v[104:105], v93 offset:50696
	ds_read_b64_tr_b16 v[106:107], v93 offset:52808
	ds_read_b128 v[108:111], v94 offset:192
	s_waitcnt lgkmcnt(0)
	v_mfma_f32_16x16x32_bf16 v[112:115], v[46:49], v[108:111], v[54:57]
	v_mfma_f32_16x16x32_bf16 v[108:111], v[104:107], v[108:111], v[50:53]
	s_nop 2
	ds_read_b128 v[50:53], v94 offset:4544
	s_waitcnt lgkmcnt(0)
	v_mfma_f32_16x16x32_bf16 v[66:69], v[46:49], v[50:53], v[66:69]
	v_mfma_f32_16x16x32_bf16 v[62:65], v[104:107], v[50:53], v[62:65]
	ds_read_b128 v[50:53], v94 offset:8896
	s_nop 5
	v_pk_mul_f32 v[66:67], v[66:67], s[4:5] op_sel_hi:[1,0]
	v_pk_mul_f32 v[68:69], v[68:69], s[4:5] op_sel_hi:[1,0]
	s_waitcnt lgkmcnt(0)
	v_mfma_f32_16x16x32_bf16 v[54:57], v[46:49], v[50:53], v[96:99]
	s_nop 2
	v_mul_f32_e32 v98, 0xbfb8aa3b, v95
	v_mul_f32_e32 v99, 0xbfb8aa3b, v70
	v_mfma_f32_16x16x32_bf16 v[50:53], v[104:107], v[50:53], v[86:89]
	v_exp_f32_e32 v98, v98
	v_exp_f32_e32 v99, v99
	v_pk_mul_f32 v[96:97], v[112:113], s[4:5] op_sel_hi:[1,0]
	ds_read_b128 v[86:89], v94 offset:13248
	s_waitcnt lgkmcnt(0)
	v_mfma_f32_16x16x32_bf16 v[46:49], v[46:49], v[86:89], v[38:41]
	v_add_f32_e64 v98, v98, 1.0
	v_add_f32_e64 v99, v99, 1.0
	v_pk_mul_f32 v[62:63], v[62:63], s[4:5] op_sel_hi:[1,0]
	v_pk_mul_f32 v[64:65], v[64:65], s[4:5] op_sel_hi:[1,0]
	v_mfma_f32_16x16x32_bf16 v[38:41], v[104:107], v[86:89], v[100:103]
	v_lshl_add_u32 v86, s20, 8, v91
	v_pk_mul_f32 v[88:89], v[114:115], s[4:5] op_sel_hi:[1,0]
	v_ashrrev_i32_e32 v87, 31, v86
	v_pk_mul_f32 v[54:55], v[54:55], s[4:5] op_sel_hi:[1,0]
	v_pk_mul_f32 v[56:57], v[56:57], s[4:5] op_sel_hi:[1,0]
	v_pk_mul_f32 v[50:51], v[50:51], s[4:5] op_sel_hi:[1,0]
	v_rcp_f32_e32 v100, v99
	s_nop 0
	v_mul_f32_e32 v99, v70, v100
	v_pk_mul_f32 v[52:53], v[52:53], s[4:5] op_sel_hi:[1,0]
	s_nop 1
	v_pk_mul_f32 v[38:39], v[38:39], s[4:5] op_sel_hi:[1,0]
	v_pk_mul_f32 v[40:41], v[40:41], s[4:5] op_sel_hi:[1,0]
	v_rcp_f32_e32 v70, v98
	s_nop 0
	v_mul_f32_e32 v98, v95, v70
	v_pk_mul_f32 v[96:97], v[98:99], v[96:97]
	v_lshlrev_b32_e32 v95, 16, v71
	v_and_b32_e32 v71, 0xffff0000, v71
	v_cvt_pk_bf16_f32 v70, v96, v97
	v_mul_f32_e32 v96, 0xbfb8aa3b, v95
	v_mul_f32_e32 v97, 0xbfb8aa3b, v71
	v_exp_f32_e32 v96, v96
	v_exp_f32_e32 v97, v97
	s_nop 0
	v_pk_add_f32 v[96:97], v[96:97], 1.0 op_sel_hi:[1,0]
	s_nop 0
	v_rcp_f32_e32 v98, v97
	s_nop 0
	v_mul_f32_e32 v97, v71, v98
	v_rcp_f32_e32 v71, v96
	s_nop 0
	v_mul_f32_e32 v96, v95, v71
	v_lshlrev_b32_e32 v95, 16, v72
	v_and_b32_e32 v72, 0xffff0000, v72
	v_mul_f32_e32 v98, 0xbfb8aa3b, v95
	v_mul_f32_e32 v99, 0xbfb8aa3b, v72
	v_exp_f32_e32 v98, v98
	v_exp_f32_e32 v99, v99
	v_pk_mul_f32 v[88:89], v[96:97], v[88:89]
	v_pk_mul_f32 v[96:97], v[108:109], s[4:5] op_sel_hi:[1,0]
	v_cvt_pk_bf16_f32 v71, v88, v89
	v_pk_add_f32 v[98:99], v[98:99], 1.0 op_sel_hi:[1,0]
	v_pk_mul_f32 v[88:89], v[110:111], s[4:5] op_sel_hi:[1,0]
	v_rcp_f32_e32 v100, v99
	s_nop 0
	v_mul_f32_e32 v99, v72, v100
	v_rcp_f32_e32 v72, v98
	s_nop 0
	v_mul_f32_e32 v98, v95, v72
	v_pk_mul_f32 v[96:97], v[98:99], v[96:97]
	v_lshlrev_b32_e32 v95, 16, v73
	v_and_b32_e32 v73, 0xffff0000, v73
	v_cvt_pk_bf16_f32 v72, v96, v97
	v_mul_f32_e32 v96, 0xbfb8aa3b, v95
	v_mul_f32_e32 v97, 0xbfb8aa3b, v73
	v_exp_f32_e32 v96, v96
	v_exp_f32_e32 v97, v97
	s_nop 0
	v_pk_add_f32 v[96:97], v[96:97], 1.0 op_sel_hi:[1,0]
	s_nop 0
	v_rcp_f32_e32 v98, v97
	s_nop 0
	v_mul_f32_e32 v97, v73, v98
	v_rcp_f32_e32 v73, v96
	s_nop 0
	v_mul_f32_e32 v96, v95, v73
	v_pk_mul_f32 v[88:89], v[96:97], v[88:89]
	s_nop 0
	v_cvt_pk_bf16_f32 v73, v88, v89
	v_lshl_add_u64 v[88:89], s[18:19], 0, v[82:83]
	v_lshlrev_b64 v[82:83], 1, v[86:87]
	v_lshl_add_u64 v[86:87], v[88:89], 0, v[82:83]
	global_store_dwordx4 v[86:87], v[70:73], off offset:1024
	s_nop 0
	s_nop 0
	v_lshlrev_b32_e32 v72, 16, v58
	v_and_b32_e32 v58, 0xffff0000, v58
	v_mul_f32_e32 v70, 0xbfb8aa3b, v72
	v_mul_f32_e32 v71, 0xbfb8aa3b, v58
	v_exp_f32_e32 v70, v70
	v_exp_f32_e32 v71, v71
	s_nop 0
	v_pk_add_f32 v[70:71], v[70:71], 1.0 op_sel_hi:[1,0]
	s_nop 0
	v_rcp_f32_e32 v73, v71
	s_nop 0
	v_mul_f32_e32 v71, v58, v73
	v_rcp_f32_e32 v58, v70
	s_nop 0
	v_mul_f32_e32 v70, v72, v58
	v_pk_mul_f32 v[66:67], v[70:71], v[66:67]
	v_lshlrev_b32_e32 v70, 16, v59
	v_and_b32_e32 v59, 0xffff0000, v59
	v_cvt_pk_bf16_f32 v58, v66, v67
	v_mul_f32_e32 v66, 0xbfb8aa3b, v70
	v_mul_f32_e32 v67, 0xbfb8aa3b, v59
	v_exp_f32_e32 v66, v66
	v_exp_f32_e32 v67, v67
	s_nop 0
	v_pk_add_f32 v[66:67], v[66:67], 1.0 op_sel_hi:[1,0]
	s_nop 0
	v_rcp_f32_e32 v71, v67
	s_nop 0
	v_mul_f32_e32 v67, v59, v71
	v_rcp_f32_e32 v59, v66
	s_nop 0
	v_mul_f32_e32 v66, v70, v59
	v_pk_mul_f32 v[66:67], v[66:67], v[68:69]
	v_lshlrev_b32_e32 v68, 16, v60
	v_and_b32_e32 v60, 0xffff0000, v60
	v_cvt_pk_bf16_f32 v59, v66, v67
	v_mul_f32_e32 v66, 0xbfb8aa3b, v68
	v_mul_f32_e32 v67, 0xbfb8aa3b, v60
	v_exp_f32_e32 v66, v66
	v_exp_f32_e32 v67, v67
	s_nop 0
	v_pk_add_f32 v[66:67], v[66:67], 1.0 op_sel_hi:[1,0]
	s_nop 0
	v_rcp_f32_e32 v69, v67
	s_nop 0
	v_mul_f32_e32 v67, v60, v69
	v_rcp_f32_e32 v60, v66
	s_nop 0
	v_mul_f32_e32 v66, v68, v60
	v_pk_mul_f32 v[62:63], v[66:67], v[62:63]
	v_lshlrev_b32_e32 v66, 16, v61
	v_and_b32_e32 v61, 0xffff0000, v61
	v_cvt_pk_bf16_f32 v60, v62, v63
	v_mul_f32_e32 v62, 0xbfb8aa3b, v66
	v_mul_f32_e32 v63, 0xbfb8aa3b, v61
	v_exp_f32_e32 v62, v62
	v_exp_f32_e32 v63, v63
	s_nop 0
	v_pk_add_f32 v[62:63], v[62:63], 1.0 op_sel_hi:[1,0]
	s_nop 0
	v_rcp_f32_e32 v67, v63
	s_nop 0
	v_mul_f32_e32 v63, v61, v67
	v_rcp_f32_e32 v61, v62
	s_nop 0
	v_mul_f32_e32 v62, v66, v61
	v_pk_mul_f32 v[62:63], v[62:63], v[64:65]
	s_nop 0
	v_cvt_pk_bf16_f32 v61, v62, v63
	v_lshlrev_b64 v[62:63], 11, v[84:85]
	v_lshl_add_u64 v[62:63], s[18:19], 0, v[62:63]
	v_lshl_add_u64 v[62:63], v[62:63], 0, v[82:83]
	global_store_dwordx4 v[62:63], v[58:61], off offset:1024
	s_nop 0
	s_nop 0
	v_lshlrev_b32_e32 v60, 16, v42
	v_and_b32_e32 v42, 0xffff0000, v42
	v_mul_f32_e32 v58, 0xbfb8aa3b, v60
	v_mul_f32_e32 v59, 0xbfb8aa3b, v42
	v_exp_f32_e32 v58, v58
	v_exp_f32_e32 v59, v59
	s_nop 0
	v_pk_add_f32 v[58:59], v[58:59], 1.0 op_sel_hi:[1,0]
	s_nop 0
	v_rcp_f32_e32 v61, v59
	s_nop 0
	v_mul_f32_e32 v59, v42, v61
	v_rcp_f32_e32 v42, v58
	s_nop 0
	v_mul_f32_e32 v58, v60, v42
	v_pk_mul_f32 v[54:55], v[58:59], v[54:55]
	v_lshlrev_b32_e32 v58, 16, v43
	v_and_b32_e32 v43, 0xffff0000, v43
	v_cvt_pk_bf16_f32 v42, v54, v55
	v_mul_f32_e32 v54, 0xbfb8aa3b, v58
	v_mul_f32_e32 v55, 0xbfb8aa3b, v43
	v_exp_f32_e32 v54, v54
	v_exp_f32_e32 v55, v55
	s_nop 0
	v_pk_add_f32 v[54:55], v[54:55], 1.0 op_sel_hi:[1,0]
	s_nop 0
	v_rcp_f32_e32 v59, v55
	s_nop 0
	v_mul_f32_e32 v55, v43, v59
	v_rcp_f32_e32 v43, v54
	s_nop 0
	v_mul_f32_e32 v54, v58, v43
	v_pk_mul_f32 v[54:55], v[54:55], v[56:57]
	v_lshlrev_b32_e32 v56, 16, v44
	v_and_b32_e32 v44, 0xffff0000, v44
	v_cvt_pk_bf16_f32 v43, v54, v55
	v_mul_f32_e32 v54, 0xbfb8aa3b, v56
	v_mul_f32_e32 v55, 0xbfb8aa3b, v44
	v_exp_f32_e32 v54, v54
	v_exp_f32_e32 v55, v55
	s_nop 0
	v_pk_add_f32 v[54:55], v[54:55], 1.0 op_sel_hi:[1,0]
	s_nop 0
	v_rcp_f32_e32 v57, v55
	s_nop 0
	v_mul_f32_e32 v55, v44, v57
	v_rcp_f32_e32 v44, v54
	s_nop 0
	v_mul_f32_e32 v54, v56, v44
	v_pk_mul_f32 v[50:51], v[54:55], v[50:51]
	v_lshlrev_b32_e32 v54, 16, v45
	v_and_b32_e32 v45, 0xffff0000, v45
	v_cvt_pk_bf16_f32 v44, v50, v51
	v_mul_f32_e32 v50, 0xbfb8aa3b, v54
	v_mul_f32_e32 v51, 0xbfb8aa3b, v45
	v_exp_f32_e32 v50, v50
	v_exp_f32_e32 v51, v51
	s_nop 0
	v_pk_add_f32 v[50:51], v[50:51], 1.0 op_sel_hi:[1,0]
	s_nop 0
	v_rcp_f32_e32 v55, v51
	s_nop 0
	v_mul_f32_e32 v51, v45, v55
	v_rcp_f32_e32 v45, v50
	s_nop 0
	v_mul_f32_e32 v50, v54, v45
	v_pk_mul_f32 v[50:51], v[50:51], v[52:53]
	s_nop 0
	v_cvt_pk_bf16_f32 v45, v50, v51
	v_lshlrev_b64 v[50:51], 11, v[80:81]
	v_lshl_add_u64 v[50:51], s[18:19], 0, v[50:51]
	v_lshl_add_u64 v[50:51], v[50:51], 0, v[82:83]
	global_store_dwordx4 v[50:51], v[42:45], off offset:1024
	s_nop 1
	v_pk_mul_f32 v[42:43], v[48:49], s[4:5] op_sel_hi:[1,0]
	v_lshlrev_b32_e32 v48, 16, v34
	v_and_b32_e32 v34, 0xffff0000, v34
	v_pk_mul_f32 v[44:45], v[46:47], s[4:5] op_sel_hi:[1,0]
	v_mul_f32_e32 v46, 0xbfb8aa3b, v48
	v_mul_f32_e32 v47, 0xbfb8aa3b, v34
	v_exp_f32_e32 v46, v46
	v_exp_f32_e32 v47, v47
	s_nop 0
	v_pk_add_f32 v[46:47], v[46:47], 1.0 op_sel_hi:[1,0]
	s_nop 0
	v_rcp_f32_e32 v49, v47
	s_nop 0
	v_mul_f32_e32 v47, v34, v49
	v_rcp_f32_e32 v34, v46
	s_nop 0
	v_mul_f32_e32 v46, v48, v34
	v_pk_mul_f32 v[44:45], v[46:47], v[44:45]
	v_lshlrev_b32_e32 v46, 16, v35
	v_and_b32_e32 v35, 0xffff0000, v35
	v_cvt_pk_bf16_f32 v34, v44, v45
	v_mul_f32_e32 v44, 0xbfb8aa3b, v46
	v_mul_f32_e32 v45, 0xbfb8aa3b, v35
	v_exp_f32_e32 v44, v44
	v_exp_f32_e32 v45, v45
	s_nop 0
	v_pk_add_f32 v[44:45], v[44:45], 1.0 op_sel_hi:[1,0]
	s_nop 0
	v_rcp_f32_e32 v47, v45
	s_nop 0
	v_mul_f32_e32 v45, v35, v47
	v_rcp_f32_e32 v35, v44
	s_nop 0
	v_mul_f32_e32 v44, v46, v35
	v_pk_mul_f32 v[42:43], v[44:45], v[42:43]
	v_lshlrev_b32_e32 v44, 16, v36
	v_and_b32_e32 v36, 0xffff0000, v36
	v_cvt_pk_bf16_f32 v35, v42, v43
	v_mul_f32_e32 v42, 0xbfb8aa3b, v44
	v_mul_f32_e32 v43, 0xbfb8aa3b, v36
	v_exp_f32_e32 v42, v42
	v_exp_f32_e32 v43, v43
	s_nop 0
	v_pk_add_f32 v[42:43], v[42:43], 1.0 op_sel_hi:[1,0]
	s_nop 0
	v_rcp_f32_e32 v45, v43
	s_nop 0
	v_mul_f32_e32 v43, v36, v45
	v_rcp_f32_e32 v36, v42
	s_nop 0
	v_mul_f32_e32 v42, v44, v36
	v_pk_mul_f32 v[38:39], v[42:43], v[38:39]
	v_lshlrev_b32_e32 v42, 16, v37
	v_and_b32_e32 v37, 0xffff0000, v37
	v_cvt_pk_bf16_f32 v36, v38, v39
	v_mul_f32_e32 v38, 0xbfb8aa3b, v42
	v_mul_f32_e32 v39, 0xbfb8aa3b, v37
	v_exp_f32_e32 v38, v38
	v_exp_f32_e32 v39, v39
	s_nop 0
	v_pk_add_f32 v[38:39], v[38:39], 1.0 op_sel_hi:[1,0]
	s_nop 0
	v_rcp_f32_e32 v43, v39
	s_nop 0
	v_mul_f32_e32 v39, v37, v43
	v_rcp_f32_e32 v37, v38
	s_nop 0
	v_mul_f32_e32 v38, v42, v37
	v_pk_mul_f32 v[38:39], v[38:39], v[40:41]
	s_and_b64 vcc, s[6:7], exec
	v_cvt_pk_bf16_f32 v37, v38, v39
	v_lshlrev_b64 v[38:39], 11, v[78:79]
	v_lshl_add_u64 v[38:39], s[18:19], 0, v[38:39]
	v_lshl_add_u64 v[38:39], v[38:39], 0, v[82:83]
	global_store_dwordx4 v[38:39], v[34:37], off offset:1024
	s_cbranch_vccnz .LBB0_308

.LBB0_311:
	s_nop 0
	v_lshl_add_u64 v[10:11], s[34:35], 0, v[52:53]
	v_add_co_u32_e32 v60, vcc, 0x27000000, v10
	v_lshl_add_u64 v[74:75], s[34:35], 0, v[54:55]
	s_nop 0
	v_addc_co_u32_e32 v61, vcc, 0, v11, vcc
	v_add_co_u32_e32 v72, vcc, 0x2b000000, v10
	global_load_dwordx4 v[46:49], v[60:61], off nt
	s_nop 0
	v_addc_co_u32_e32 v73, vcc, 0, v11, vcc
	global_load_dwordx4 v[56:59], v[72:73], off nt
	global_load_dwordx4 v[68:71], v[74:75], off offset:-256 nt
	global_load_dwordx4 v[42:45], v[60:61], off offset:1024 nt
	global_load_dwordx4 v[38:41], v[72:73], off offset:1024 nt
	global_load_dwordx4 v[34:37], v[74:75], off offset:-128 nt
	global_load_dwordx4 v[30:33], v[60:61], off offset:2048 nt
	global_load_dwordx4 v[26:29], v[72:73], off offset:2048 nt
	global_load_dwordx4 v[22:25], v[74:75], off nt
	global_load_dwordx4 v[18:21], v[60:61], off offset:3072 nt
	global_load_dwordx4 v[14:17], v[72:73], off offset:3072 nt
	global_load_dwordx4 v[10:13], v[74:75], off offset:128 nt
	s_add_i32 s4, s4, s6
	v_lshl_add_u64 v[52:53], v[52:53], 0, s[10:11]
	v_lshl_add_u64 v[54:55], v[54:55], 0, s[12:13]
	s_cmp_lt_i32 s4, 0x10000
	s_waitcnt vmcnt(9)
	v_lshlrev_b32_e32 v67, 16, v70
	v_and_b32_e32 v70, 0xffff0000, v70
	v_lshlrev_b32_e32 v60, 16, v49
	v_and_b32_e32 v61, 0xffff0000, v49
	v_lshlrev_b32_e32 v72, 16, v59
	v_and_b32_e32 v73, 0xffff0000, v59
	v_pk_add_f32 v[60:61], v[60:61], v[72:73]
	v_lshlrev_b32_e32 v72, 16, v48
	v_and_b32_e32 v73, 0xffff0000, v48
	v_lshlrev_b32_e32 v48, 16, v58
	v_and_b32_e32 v49, 0xffff0000, v58
	v_pk_add_f32 v[48:49], v[72:73], v[48:49]
	v_mov_b32_e32 v58, v60
	v_mov_b32_e32 v59, v48
	v_pk_mul_f32 v[58:59], v[58:59], v[58:59]
	v_mov_b32_e32 v72, v61
	v_mov_b32_e32 v73, v49
	v_pk_fma_f32 v[58:59], v[72:73], v[72:73], v[58:59]
	v_mul_f32_e32 v72, 0xbfb8aa3b, v67
	v_mul_f32_e32 v73, 0xbfb8aa3b, v70
	v_exp_f32_e32 v72, v72
	v_exp_f32_e32 v73, v73
	s_nop 0
	v_pk_add_f32 v[72:73], v[72:73], 1.0 op_sel_hi:[1,0]
	s_nop 0
	v_rcp_f32_e32 v74, v73
	s_nop 0
	v_mul_f32_e32 v73, v70, v74
	v_lshlrev_b32_e32 v74, 16, v47
	v_and_b32_e32 v75, 0xffff0000, v47
	v_lshlrev_b32_e32 v47, 16, v69
	v_rcp_f32_e32 v70, v72
	s_nop 0
	v_mul_f32_e32 v72, v67, v70
	v_lshlrev_b32_e32 v76, 16, v57
	v_and_b32_e32 v77, 0xffff0000, v57
	v_and_b32_e32 v57, 0xffff0000, v69
	v_mul_f32_e32 v67, 0xbfb8aa3b, v47
	v_pk_add_f32 v[74:75], v[74:75], v[76:77]
	v_exp_f32_e32 v76, v67
	v_mul_f32_e32 v67, 0xbfb8aa3b, v57
	v_exp_f32_e32 v77, v67
	s_nop 0
	v_pk_add_f32 v[76:77], v[76:77], 1.0 op_sel_hi:[1,0]
	s_nop 0
	v_rcp_f32_e32 v67, v77
	s_nop 0
	v_mul_f32_e32 v77, v57, v67
	v_and_b32_e32 v79, 0xffff0000, v46
	v_rcp_f32_e32 v57, v76
	s_nop 0
	v_mul_f32_e32 v76, v47, v57
	v_lshlrev_b32_e32 v78, 16, v46
	v_lshlrev_b32_e32 v46, 16, v56
	v_and_b32_e32 v47, 0xffff0000, v56
	v_pk_add_f32 v[46:47], v[78:79], v[46:47]
	v_mov_b32_e32 v57, v74
	v_mov_b32_e32 v56, v46
	v_pk_mul_f32 v[56:57], v[56:57], v[56:57]
	v_mov_b32_e32 v78, v47
	v_mov_b32_e32 v79, v75
	v_lshlrev_b32_e32 v67, 16, v68
	v_and_b32_e32 v70, 0xffff0000, v68
	v_pk_fma_f32 v[56:57], v[78:79], v[78:79], v[56:57]
	v_mul_f32_e32 v68, 0xbfb8aa3b, v67
	v_mul_f32_e32 v69, 0xbfb8aa3b, v70
	v_exp_f32_e32 v68, v68
	v_exp_f32_e32 v69, v69
	v_add_f32_e32 v56, v56, v57
	v_add_f32_e32 v56, v59, v56
	v_add_f32_e32 v56, v58, v56
	ds_bpermute_b32 v57, v1, v56
	v_pk_add_f32 v[68:69], v[68:69], 1.0 op_sel_hi:[1,0]
	s_waitcnt lgkmcnt(0)
	v_add_f32_e32 v56, v56, v57
	ds_bpermute_b32 v57, v62, v56
	s_waitcnt lgkmcnt(0)
	v_add_f32_e32 v56, v56, v57
	ds_bpermute_b32 v57, v63, v56
	v_rcp_f32_e32 v78, v69
	s_nop 0
	v_mul_f32_e32 v69, v70, v78
	s_waitcnt lgkmcnt(0)
	v_add_f32_e32 v56, v56, v57
	ds_bpermute_b32 v57, v64, v56
	s_waitcnt lgkmcnt(0)
	v_add_f32_e32 v56, v56, v57
	v_fmamk_f32 v56, v56, 0x3c000000, v65
	v_cmp_gt_f32_e32 vcc, s5, v56
	v_mul_f32_e32 v57, 0x4f800000, v56
	v_rcp_f32_e32 v70, v68
	s_nop 0
	v_mul_f32_e32 v68, v67, v70
	v_cndmask_b32_e32 v56, v56, v57, vcc
	v_sqrt_f32_e32 v57, v56
	s_nop 0
	v_add_u32_e32 v58, -1, v57
	v_fma_f32 v59, -v58, v57, v56
	v_cmp_ge_f32_e64 s[0:1], 0, v59
	v_add_u32_e32 v59, 1, v57
	s_nop 0
	v_cndmask_b32_e64 v58, v57, v58, s[0:1]
	v_fma_f32 v57, -v59, v57, v56
	v_cmp_lt_f32_e64 s[0:1], 0, v57
	s_nop 1
	v_cndmask_b32_e64 v57, v58, v59, s[0:1]
	v_mul_f32_e32 v58, 0x37800000, v57
	v_cndmask_b32_e32 v57, v57, v58, vcc
	v_cmp_class_f32_e32 vcc, v56, v66
	s_nop 1
	v_cndmask_b32_e32 v56, v57, v56, vcc
	v_rcp_f32_e32 v56, v56
	s_nop 0
	v_pk_mul_f32 v[48:49], v[48:49], v[56:57] op_sel_hi:[1,0]
	v_pk_mul_f32 v[46:47], v[46:47], v[56:57] op_sel_hi:[1,0]
	v_pk_mul_f32 v[58:59], v[74:75], v[56:57] op_sel_hi:[1,0]
	v_pk_mul_f32 v[48:49], v[6:7], v[48:49]
	v_pk_mul_f32 v[46:47], v[2:3], v[46:47]
	v_pk_mul_f32 v[58:59], v[4:5], v[58:59]
	v_pk_mul_f32 v[48:49], v[72:73], v[48:49]
	v_pk_mul_f32 v[46:47], v[68:69], v[46:47]
	v_pk_mul_f32 v[58:59], v[76:77], v[58:59]
	v_cvt_pk_bf16_f32 v48, v48, v49
	v_lshlrev_b32_e32 v49, 16, v71
	v_and_b32_e32 v67, 0xffff0000, v71
	v_cvt_pk_bf16_f32 v46, v46, v47
	v_cvt_pk_bf16_f32 v47, v58, v59
	v_mul_f32_e32 v57, 0xbfb8aa3b, v49
	v_mul_f32_e32 v59, 0xbfb8aa3b, v67
	v_exp_f32_e32 v58, v57
	v_exp_f32_e32 v59, v59
	v_pk_mul_f32 v[56:57], v[60:61], v[56:57] op_sel_hi:[1,0]
	v_pk_add_f32 v[58:59], v[58:59], 1.0 op_sel_hi:[1,0]
	s_nop 0
	v_pk_mul_f32 v[56:57], v[8:9], v[56:57]
	v_rcp_f32_e32 v60, v59
	s_nop 0
	v_mul_f32_e32 v59, v67, v60
	v_rcp_f32_e32 v60, v58
	s_nop 0
	v_mul_f32_e32 v58, v49, v60
	v_pk_mul_f32 v[56:57], v[58:59], v[56:57]
	s_waitcnt vmcnt(6)
	v_lshlrev_b32_e32 v60, 16, v36
	v_cvt_pk_bf16_f32 v49, v56, v57
	v_lshl_add_u64 v[56:57], s[34:35], 0, v[50:51]
	v_add_co_u32_e32 v58, vcc, s7, v56
	v_and_b32_e32 v36, 0xffff0000, v36
	s_nop 0
	v_addc_co_u32_e32 v59, vcc, 0, v57, vcc
	v_add_co_u32_e32 v56, vcc, s14, v56
	v_lshl_add_u64 v[50:51], v[50:51], 0, s[8:9]
	s_nop 0
	v_addc_co_u32_e32 v57, vcc, 0, v57, vcc
	global_store_dwordx4 v[56:57], v[46:49], off offset:-4096
	s_nop 1
	v_lshlrev_b32_e32 v46, 16, v45
	v_and_b32_e32 v47, 0xffff0000, v45
	v_lshlrev_b32_e32 v48, 16, v41
	v_and_b32_e32 v49, 0xffff0000, v41
	v_pk_add_f32 v[46:47], v[46:47], v[48:49]
	v_lshlrev_b32_e32 v48, 16, v44
	v_and_b32_e32 v49, 0xffff0000, v44
	v_lshlrev_b32_e32 v44, 16, v40
	v_and_b32_e32 v45, 0xffff0000, v40
	v_pk_add_f32 v[40:41], v[48:49], v[44:45]
	v_mov_b32_e32 v44, v46
	v_mov_b32_e32 v45, v40
	v_pk_mul_f32 v[44:45], v[44:45], v[44:45]
	v_mov_b32_e32 v48, v47
	v_mov_b32_e32 v49, v41
	v_pk_fma_f32 v[44:45], v[48:49], v[48:49], v[44:45]
	v_mul_f32_e32 v48, 0xbfb8aa3b, v60
	v_mul_f32_e32 v49, 0xbfb8aa3b, v36
	v_exp_f32_e32 v48, v48
	v_exp_f32_e32 v49, v49
	s_nop 0
	v_pk_add_f32 v[48:49], v[48:49], 1.0 op_sel_hi:[1,0]
	s_nop 0
	v_rcp_f32_e32 v61, v49
	s_nop 0
	v_mul_f32_e32 v49, v36, v61
	v_rcp_f32_e32 v36, v48
	s_nop 0
	v_mul_f32_e32 v48, v60, v36
	v_lshlrev_b32_e32 v36, 16, v35
	v_lshlrev_b32_e32 v60, 16, v43
	v_and_b32_e32 v61, 0xffff0000, v43
	v_lshlrev_b32_e32 v68, 16, v39
	v_and_b32_e32 v69, 0xffff0000, v39
	v_and_b32_e32 v35, 0xffff0000, v35
	v_mul_f32_e32 v39, 0xbfb8aa3b, v36
	v_pk_add_f32 v[60:61], v[60:61], v[68:69]
	v_exp_f32_e32 v68, v39
	v_mul_f32_e32 v39, 0xbfb8aa3b, v35
	v_exp_f32_e32 v69, v39
	s_nop 0
	v_pk_add_f32 v[68:69], v[68:69], 1.0 op_sel_hi:[1,0]
	s_nop 0
	v_rcp_f32_e32 v39, v69
	s_nop 0
	v_mul_f32_e32 v69, v35, v39
	v_and_b32_e32 v71, 0xffff0000, v42
	v_rcp_f32_e32 v35, v68
	s_nop 0
	v_mul_f32_e32 v68, v36, v35
	v_lshlrev_b32_e32 v36, 16, v34
	v_and_b32_e32 v67, 0xffff0000, v34
	v_mul_f32_e32 v34, 0xbfb8aa3b, v36
	v_mul_f32_e32 v35, 0xbfb8aa3b, v67
	v_exp_f32_e32 v34, v34
	v_exp_f32_e32 v35, v35
	v_lshlrev_b32_e32 v70, 16, v42
	v_lshlrev_b32_e32 v42, 16, v38
	v_and_b32_e32 v43, 0xffff0000, v38
	v_pk_add_f32 v[42:43], v[70:71], v[42:43]
	v_mov_b32_e32 v39, v60
	v_mov_b32_e32 v38, v42
	v_pk_mul_f32 v[38:39], v[38:39], v[38:39]
	v_mov_b32_e32 v70, v43
	v_mov_b32_e32 v71, v61
	v_pk_add_f32 v[34:35], v[34:35], 1.0 op_sel_hi:[1,0]
	v_pk_fma_f32 v[38:39], v[70:71], v[70:71], v[38:39]
	v_rcp_f32_e32 v70, v35
	s_nop 0
	v_mul_f32_e32 v35, v67, v70
	v_rcp_f32_e32 v67, v34
	s_nop 0
	v_mul_f32_e32 v34, v36, v67
	v_add_f32_e32 v36, v38, v39
	v_add_f32_e32 v36, v45, v36
	v_add_f32_e32 v36, v44, v36
	ds_bpermute_b32 v38, v1, v36
	s_waitcnt lgkmcnt(0)
	v_add_f32_e32 v36, v36, v38
	ds_bpermute_b32 v38, v62, v36
	s_waitcnt lgkmcnt(0)
	v_add_f32_e32 v36, v36, v38
	ds_bpermute_b32 v38, v63, v36
	s_waitcnt lgkmcnt(0)
	v_add_f32_e32 v36, v36, v38
	ds_bpermute_b32 v38, v64, v36
	s_waitcnt lgkmcnt(0)
	v_add_f32_e32 v36, v36, v38
	v_fmamk_f32 v36, v36, 0x3c000000, v65
	v_cmp_gt_f32_e32 vcc, s5, v36
	v_mul_f32_e32 v38, 0x4f800000, v36
	s_nop 0
	v_cndmask_b32_e32 v36, v36, v38, vcc
	v_sqrt_f32_e32 v38, v36
	s_nop 0
	v_add_u32_e32 v39, -1, v38
	v_fma_f32 v44, -v39, v38, v36
	v_cmp_ge_f32_e64 s[0:1], 0, v44
	v_add_u32_e32 v44, 1, v38
	s_nop 0
	v_cndmask_b32_e64 v39, v38, v39, s[0:1]
	v_fma_f32 v38, -v44, v38, v36
	v_cmp_lt_f32_e64 s[0:1], 0, v38
	s_nop 1
	v_cndmask_b32_e64 v38, v39, v44, s[0:1]
	v_mul_f32_e32 v39, 0x37800000, v38
	v_cndmask_b32_e32 v38, v38, v39, vcc
	v_cmp_class_f32_e32 vcc, v36, v66
	s_nop 1
	v_cndmask_b32_e32 v36, v38, v36, vcc
	v_rcp_f32_e32 v38, v36
	s_nop 0
	v_pk_mul_f32 v[42:43], v[42:43], v[38:39] op_sel_hi:[1,0]
	v_pk_mul_f32 v[40:41], v[40:41], v[38:39] op_sel_hi:[1,0]
	v_pk_mul_f32 v[42:43], v[2:3], v[42:43]
	v_pk_mul_f32 v[40:41], v[6:7], v[40:41]
	v_pk_mul_f32 v[34:35], v[34:35], v[42:43]
	v_pk_mul_f32 v[42:43], v[60:61], v[38:39] op_sel_hi:[1,0]
	v_cvt_pk_bf16_f32 v34, v34, v35
	v_pk_mul_f32 v[42:43], v[4:5], v[42:43]
	v_pk_mul_f32 v[40:41], v[48:49], v[40:41]
	v_pk_mul_f32 v[42:43], v[68:69], v[42:43]
	v_cvt_pk_bf16_f32 v36, v40, v41
	v_cvt_pk_bf16_f32 v35, v42, v43
	v_lshlrev_b32_e32 v42, 16, v37
	v_and_b32_e32 v37, 0xffff0000, v37
	v_mul_f32_e32 v39, 0xbfb8aa3b, v42
	v_mul_f32_e32 v41, 0xbfb8aa3b, v37
	v_exp_f32_e32 v40, v39
	v_exp_f32_e32 v41, v41
	v_pk_mul_f32 v[38:39], v[46:47], v[38:39] op_sel_hi:[1,0]
	v_pk_add_f32 v[40:41], v[40:41], 1.0 op_sel_hi:[1,0]
	s_nop 0
	v_pk_mul_f32 v[38:39], v[8:9], v[38:39]
	v_rcp_f32_e32 v43, v41
	s_nop 0
	v_mul_f32_e32 v41, v37, v43
	v_rcp_f32_e32 v37, v40
	s_nop 0
	v_mul_f32_e32 v40, v42, v37
	v_pk_mul_f32 v[38:39], v[40:41], v[38:39]
	s_nop 0
	v_cvt_pk_bf16_f32 v37, v38, v39
	global_store_dwordx4 v[58:59], v[34:37], off offset:2048
	s_waitcnt vmcnt(5)
	v_lshlrev_b32_e32 v38, 16, v24
	v_and_b32_e32 v24, 0xffff0000, v24
	v_lshlrev_b32_e32 v34, 16, v33
	v_and_b32_e32 v35, 0xffff0000, v33
	v_lshlrev_b32_e32 v36, 16, v29
	v_and_b32_e32 v37, 0xffff0000, v29
	v_pk_add_f32 v[34:35], v[34:35], v[36:37]
	v_lshlrev_b32_e32 v36, 16, v32
	v_and_b32_e32 v37, 0xffff0000, v32
	v_lshlrev_b32_e32 v32, 16, v28
	v_and_b32_e32 v33, 0xffff0000, v28
	v_pk_add_f32 v[28:29], v[36:37], v[32:33]
	v_mov_b32_e32 v32, v34
	v_mov_b32_e32 v33, v28
	v_pk_mul_f32 v[32:33], v[32:33], v[32:33]
	v_mov_b32_e32 v36, v35
	v_mov_b32_e32 v37, v29
	v_pk_fma_f32 v[32:33], v[36:37], v[36:37], v[32:33]
	v_mul_f32_e32 v36, 0xbfb8aa3b, v38
	v_mul_f32_e32 v37, 0xbfb8aa3b, v24
	v_exp_f32_e32 v36, v36
	v_exp_f32_e32 v37, v37
	s_nop 0
	v_pk_add_f32 v[36:37], v[36:37], 1.0 op_sel_hi:[1,0]
	s_nop 0
	v_rcp_f32_e32 v39, v37
	s_nop 0
	v_mul_f32_e32 v37, v24, v39
	v_rcp_f32_e32 v24, v36
	s_nop 0
	v_mul_f32_e32 v36, v38, v24
	v_lshlrev_b32_e32 v24, 16, v23
	v_lshlrev_b32_e32 v38, 16, v31
	v_and_b32_e32 v39, 0xffff0000, v31
	v_lshlrev_b32_e32 v40, 16, v27
	v_and_b32_e32 v41, 0xffff0000, v27
	v_and_b32_e32 v23, 0xffff0000, v23
	v_mul_f32_e32 v27, 0xbfb8aa3b, v24
	v_pk_add_f32 v[38:39], v[38:39], v[40:41]
	v_exp_f32_e32 v40, v27
	v_mul_f32_e32 v27, 0xbfb8aa3b, v23
	v_exp_f32_e32 v41, v27
	s_nop 0
	v_pk_add_f32 v[40:41], v[40:41], 1.0 op_sel_hi:[1,0]
	s_nop 0
	v_rcp_f32_e32 v27, v41
	s_nop 0
	v_mul_f32_e32 v41, v23, v27
	v_lshlrev_b32_e32 v42, 16, v30
	v_and_b32_e32 v43, 0xffff0000, v30
	v_lshlrev_b32_e32 v30, 16, v26
	v_and_b32_e32 v31, 0xffff0000, v26
	v_pk_add_f32 v[30:31], v[42:43], v[30:31]
	v_mov_b32_e32 v27, v38
	v_mov_b32_e32 v26, v30
	v_pk_mul_f32 v[26:27], v[26:27], v[26:27]
	v_mov_b32_e32 v42, v31
	v_mov_b32_e32 v43, v39
	v_rcp_f32_e32 v23, v40
	s_nop 0
	v_mul_f32_e32 v40, v24, v23
	v_pk_fma_f32 v[26:27], v[42:43], v[42:43], v[26:27]
	v_lshlrev_b32_e32 v24, 16, v22
	v_and_b32_e32 v42, 0xffff0000, v22
	v_mul_f32_e32 v22, 0xbfb8aa3b, v24
	v_mul_f32_e32 v23, 0xbfb8aa3b, v42
	v_exp_f32_e32 v22, v22
	v_exp_f32_e32 v23, v23
	s_nop 0
	v_pk_add_f32 v[22:23], v[22:23], 1.0 op_sel_hi:[1,0]
	s_nop 0
	v_rcp_f32_e32 v43, v23
	s_nop 0
	v_mul_f32_e32 v23, v42, v43
	v_rcp_f32_e32 v42, v22
	s_nop 0
	v_mul_f32_e32 v22, v24, v42
	v_add_f32_e32 v24, v26, v27
	v_add_f32_e32 v24, v33, v24
	v_add_f32_e32 v24, v32, v24
	ds_bpermute_b32 v26, v1, v24
	s_waitcnt lgkmcnt(0)
	v_add_f32_e32 v24, v24, v26
	ds_bpermute_b32 v26, v62, v24
	s_waitcnt lgkmcnt(0)
	v_add_f32_e32 v24, v24, v26
	ds_bpermute_b32 v26, v63, v24
	s_waitcnt lgkmcnt(0)
	v_add_f32_e32 v24, v24, v26
	ds_bpermute_b32 v26, v64, v24
	s_waitcnt lgkmcnt(0)
	v_add_f32_e32 v24, v24, v26
	v_fmamk_f32 v24, v24, 0x3c000000, v65
	v_cmp_gt_f32_e32 vcc, s5, v24
	v_mul_f32_e32 v26, 0x4f800000, v24
	s_nop 0
	v_cndmask_b32_e32 v24, v24, v26, vcc
	v_sqrt_f32_e32 v26, v24
	s_nop 0
	v_add_u32_e32 v27, -1, v26
	v_fma_f32 v32, -v27, v26, v24
	v_cmp_ge_f32_e64 s[0:1], 0, v32
	v_add_u32_e32 v32, 1, v26
	s_nop 0
	v_cndmask_b32_e64 v27, v26, v27, s[0:1]
	v_fma_f32 v26, -v32, v26, v24
	v_cmp_lt_f32_e64 s[0:1], 0, v26
	s_nop 1
	v_cndmask_b32_e64 v26, v27, v32, s[0:1]
	v_mul_f32_e32 v27, 0x37800000, v26
	v_cndmask_b32_e32 v26, v26, v27, vcc
	v_cmp_class_f32_e32 vcc, v24, v66
	s_nop 1
	v_cndmask_b32_e32 v24, v26, v24, vcc
	v_rcp_f32_e32 v26, v24
	s_nop 0
	v_pk_mul_f32 v[30:31], v[30:31], v[26:27] op_sel_hi:[1,0]
	v_pk_mul_f32 v[28:29], v[28:29], v[26:27] op_sel_hi:[1,0]
	v_pk_mul_f32 v[30:31], v[2:3], v[30:31]
	v_pk_mul_f32 v[28:29], v[6:7], v[28:29]
	v_pk_mul_f32 v[22:23], v[22:23], v[30:31]
	v_pk_mul_f32 v[30:31], v[38:39], v[26:27] op_sel_hi:[1,0]
	v_cvt_pk_bf16_f32 v22, v22, v23
	v_pk_mul_f32 v[30:31], v[4:5], v[30:31]
	v_pk_mul_f32 v[28:29], v[36:37], v[28:29]
	v_pk_mul_f32 v[30:31], v[40:41], v[30:31]
	v_cvt_pk_bf16_f32 v24, v28, v29
	v_cvt_pk_bf16_f32 v23, v30, v31
	v_lshlrev_b32_e32 v30, 16, v25
	v_and_b32_e32 v25, 0xffff0000, v25
	v_mul_f32_e32 v27, 0xbfb8aa3b, v30
	v_mul_f32_e32 v29, 0xbfb8aa3b, v25
	v_exp_f32_e32 v28, v27
	v_exp_f32_e32 v29, v29
	v_pk_mul_f32 v[26:27], v[34:35], v[26:27] op_sel_hi:[1,0]
	v_pk_add_f32 v[28:29], v[28:29], 1.0 op_sel_hi:[1,0]
	s_nop 0
	v_pk_mul_f32 v[26:27], v[8:9], v[26:27]
	v_rcp_f32_e32 v31, v29
	s_nop 0
	v_mul_f32_e32 v29, v25, v31
	v_rcp_f32_e32 v25, v28
	s_nop 0
	v_mul_f32_e32 v28, v30, v25
	v_pk_mul_f32 v[26:27], v[28:29], v[26:27]
	s_nop 0
	v_cvt_pk_bf16_f32 v25, v26, v27
	global_store_dwordx4 v[56:57], v[22:25], off
	s_waitcnt vmcnt(3)
	v_lshlrev_b32_e32 v26, 16, v12
	v_and_b32_e32 v12, 0xffff0000, v12
	v_lshlrev_b32_e32 v22, 16, v21
	v_and_b32_e32 v23, 0xffff0000, v21
	v_lshlrev_b32_e32 v24, 16, v17
	v_and_b32_e32 v25, 0xffff0000, v17
	v_pk_add_f32 v[22:23], v[22:23], v[24:25]
	v_lshlrev_b32_e32 v24, 16, v20
	v_and_b32_e32 v25, 0xffff0000, v20
	v_lshlrev_b32_e32 v20, 16, v16
	v_and_b32_e32 v21, 0xffff0000, v16
	v_pk_add_f32 v[16:17], v[24:25], v[20:21]
	v_mov_b32_e32 v20, v22
	v_mov_b32_e32 v21, v16
	v_pk_mul_f32 v[20:21], v[20:21], v[20:21]
	v_mov_b32_e32 v24, v23
	v_mov_b32_e32 v25, v17
	v_pk_fma_f32 v[20:21], v[24:25], v[24:25], v[20:21]
	v_mul_f32_e32 v24, 0xbfb8aa3b, v26
	v_mul_f32_e32 v25, 0xbfb8aa3b, v12
	v_exp_f32_e32 v24, v24
	v_exp_f32_e32 v25, v25
	s_nop 0
	v_pk_add_f32 v[24:25], v[24:25], 1.0 op_sel_hi:[1,0]
	s_nop 0
	v_rcp_f32_e32 v27, v25
	s_nop 0
	v_mul_f32_e32 v25, v12, v27
	v_rcp_f32_e32 v12, v24
	s_nop 0
	v_mul_f32_e32 v24, v26, v12
	v_lshlrev_b32_e32 v12, 16, v11
	v_lshlrev_b32_e32 v26, 16, v19
	v_and_b32_e32 v27, 0xffff0000, v19
	v_lshlrev_b32_e32 v28, 16, v15
	v_and_b32_e32 v29, 0xffff0000, v15
	v_and_b32_e32 v11, 0xffff0000, v11
	v_mul_f32_e32 v15, 0xbfb8aa3b, v12
	v_pk_add_f32 v[26:27], v[26:27], v[28:29]
	v_exp_f32_e32 v28, v15
	v_mul_f32_e32 v15, 0xbfb8aa3b, v11
	v_exp_f32_e32 v29, v15
	s_nop 0
	v_pk_add_f32 v[28:29], v[28:29], 1.0 op_sel_hi:[1,0]
	s_nop 0
	v_rcp_f32_e32 v15, v29
	s_nop 0
	v_mul_f32_e32 v29, v11, v15
	v_lshlrev_b32_e32 v30, 16, v18
	v_and_b32_e32 v31, 0xffff0000, v18
	v_lshlrev_b32_e32 v18, 16, v14
	v_and_b32_e32 v19, 0xffff0000, v14
	v_pk_add_f32 v[18:19], v[30:31], v[18:19]
	v_mov_b32_e32 v15, v26
	v_mov_b32_e32 v14, v18
	v_pk_mul_f32 v[14:15], v[14:15], v[14:15]
	v_mov_b32_e32 v30, v19
	v_mov_b32_e32 v31, v27
	v_rcp_f32_e32 v11, v28
	s_nop 0
	v_mul_f32_e32 v28, v12, v11
	v_pk_fma_f32 v[14:15], v[30:31], v[30:31], v[14:15]
	v_lshlrev_b32_e32 v12, 16, v10
	v_and_b32_e32 v30, 0xffff0000, v10
	v_mul_f32_e32 v10, 0xbfb8aa3b, v12
	v_mul_f32_e32 v11, 0xbfb8aa3b, v30
	v_exp_f32_e32 v10, v10
	v_exp_f32_e32 v11, v11
	s_nop 0
	v_pk_add_f32 v[10:11], v[10:11], 1.0 op_sel_hi:[1,0]
	s_nop 0
	v_rcp_f32_e32 v31, v11
	s_nop 0
	v_mul_f32_e32 v11, v30, v31
	v_rcp_f32_e32 v30, v10
	s_nop 0
	v_mul_f32_e32 v10, v12, v30
	v_add_f32_e32 v12, v14, v15
	v_add_f32_e32 v12, v21, v12
	v_add_f32_e32 v12, v20, v12
	ds_bpermute_b32 v14, v1, v12
	s_waitcnt lgkmcnt(0)
	v_add_f32_e32 v12, v12, v14
	ds_bpermute_b32 v14, v62, v12
	s_waitcnt lgkmcnt(0)
	v_add_f32_e32 v12, v12, v14
	ds_bpermute_b32 v14, v63, v12
	s_waitcnt lgkmcnt(0)
	v_add_f32_e32 v12, v12, v14
	ds_bpermute_b32 v14, v64, v12
	s_waitcnt lgkmcnt(0)
	v_add_f32_e32 v12, v12, v14
	v_fmamk_f32 v12, v12, 0x3c000000, v65
	v_cmp_gt_f32_e32 vcc, s5, v12
	v_mul_f32_e32 v14, 0x4f800000, v12
	s_nop 0
	v_cndmask_b32_e32 v12, v12, v14, vcc
	v_sqrt_f32_e32 v14, v12
	s_nop 0
	v_add_u32_e32 v15, -1, v14
	v_fma_f32 v20, -v15, v14, v12
	v_cmp_ge_f32_e64 s[0:1], 0, v20
	v_add_u32_e32 v20, 1, v14
	s_nop 0
	v_cndmask_b32_e64 v15, v14, v15, s[0:1]
	v_fma_f32 v14, -v20, v14, v12
	v_cmp_lt_f32_e64 s[0:1], 0, v14
	s_nop 1
	v_cndmask_b32_e64 v14, v15, v20, s[0:1]
	v_mul_f32_e32 v15, 0x37800000, v14
	v_cndmask_b32_e32 v14, v14, v15, vcc
	v_cmp_class_f32_e32 vcc, v12, v66
	s_nop 1
	v_cndmask_b32_e32 v12, v14, v12, vcc
	v_rcp_f32_e32 v14, v12
	s_nop 0
	v_pk_mul_f32 v[18:19], v[18:19], v[14:15] op_sel_hi:[1,0]
	v_pk_mul_f32 v[16:17], v[16:17], v[14:15] op_sel_hi:[1,0]
	v_pk_mul_f32 v[18:19], v[2:3], v[18:19]
	v_pk_mul_f32 v[16:17], v[6:7], v[16:17]
	v_pk_mul_f32 v[10:11], v[10:11], v[18:19]
	v_pk_mul_f32 v[18:19], v[26:27], v[14:15] op_sel_hi:[1,0]
	v_cvt_pk_bf16_f32 v10, v10, v11
	v_pk_mul_f32 v[18:19], v[4:5], v[18:19]
	v_pk_mul_f32 v[16:17], v[24:25], v[16:17]
	v_pk_mul_f32 v[18:19], v[28:29], v[18:19]
	v_cvt_pk_bf16_f32 v12, v16, v17
	v_cvt_pk_bf16_f32 v11, v18, v19
	v_lshlrev_b32_e32 v18, 16, v13
	v_and_b32_e32 v13, 0xffff0000, v13
	v_mul_f32_e32 v15, 0xbfb8aa3b, v18
	v_mul_f32_e32 v17, 0xbfb8aa3b, v13
	v_exp_f32_e32 v16, v15
	v_exp_f32_e32 v17, v17
	v_pk_mul_f32 v[14:15], v[22:23], v[14:15] op_sel_hi:[1,0]
	v_pk_add_f32 v[16:17], v[16:17], 1.0 op_sel_hi:[1,0]
	s_nop 0
	v_pk_mul_f32 v[14:15], v[8:9], v[14:15]
	v_rcp_f32_e32 v19, v17
	s_nop 0
	v_mul_f32_e32 v17, v13, v19
	v_rcp_f32_e32 v13, v16
	s_nop 0
	v_mul_f32_e32 v16, v18, v13
	v_pk_mul_f32 v[14:15], v[16:17], v[14:15]
	s_nop 0
	v_cvt_pk_bf16_f32 v13, v14, v15
	global_store_dwordx4 v[56:57], v[10:13], off offset:2048
	s_cbranch_scc1 .LBB0_311

	.amdhsa_kernel _Z10fwd_kernel4Args
		.amdhsa_group_segment_fixed_size 0
		.amdhsa_private_segment_fixed_size 0
		.amdhsa_kernarg_size 376
		.amdhsa_user_sgpr_count 2
		.amdhsa_user_sgpr_dispatch_ptr 0
		.amdhsa_user_sgpr_queue_ptr 0
		.amdhsa_user_sgpr_kernarg_segment_ptr 1
		.amdhsa_user_sgpr_dispatch_id 0
		.amdhsa_user_sgpr_kernarg_preload_length 0
		.amdhsa_user_sgpr_kernarg_preload_offset 0
		.amdhsa_user_sgpr_private_segment_size 0
		.amdhsa_uses_dynamic_stack 0
		.amdhsa_enable_private_segment 0
		.amdhsa_system_sgpr_workgroup_id_x 1
		.amdhsa_system_sgpr_workgroup_id_y 0
		.amdhsa_system_sgpr_workgroup_id_z 0
		.amdhsa_system_sgpr_workgroup_info 0
		.amdhsa_system_vgpr_workitem_id 0
		.amdhsa_next_free_vgpr 256
		.amdhsa_next_free_sgpr 100
		.amdhsa_accum_offset 256
		.amdhsa_reserve_vcc 1
		.amdhsa_float_round_mode_32 0
		.amdhsa_float_round_mode_16_64 0
		.amdhsa_float_denorm_mode_32 3
		.amdhsa_float_denorm_mode_16_64 3
		.amdhsa_dx10_clamp 1
		.amdhsa_ieee_mode 1
		.amdhsa_fp16_overflow 0
		.amdhsa_tg_split 0
		.amdhsa_exception_fp_ieee_invalid_op 0
		.amdhsa_exception_fp_denorm_src 0
		.amdhsa_exception_fp_ieee_div_zero 0
		.amdhsa_exception_fp_ieee_overflow 0
		.amdhsa_exception_fp_ieee_underflow 0
		.amdhsa_exception_fp_ieee_inexact 0
		.amdhsa_exception_int_div_zero 0
	.end_amdhsa_kernel

amdhsa.kernels:
  - .agpr_count:     0
    .args:
      - .offset:         0
        .size:           120
        .value_kind:     by_value
      - .offset:         120
        .size:           4
        .value_kind:     hidden_block_count_x
      - .offset:         124
        .size:           4
        .value_kind:     hidden_block_count_y
      - .offset:         128
        .size:           4
        .value_kind:     hidden_block_count_z
      - .offset:         132
        .size:           2
        .value_kind:     hidden_group_size_x
      - .offset:         134
        .size:           2
        .value_kind:     hidden_group_size_y
      - .offset:         136
        .size:           2
        .value_kind:     hidden_group_size_z
      - .offset:         138
        .size:           2
        .value_kind:     hidden_remainder_x
      - .offset:         140
        .size:           2
        .value_kind:     hidden_remainder_y
      - .offset:         142
        .size:           2
        .value_kind:     hidden_remainder_z
      - .offset:         160
        .size:           8
        .value_kind:     hidden_global_offset_x
      - .offset:         168
        .size:           8
        .value_kind:     hidden_global_offset_y
      - .offset:         176
        .size:           8
        .value_kind:     hidden_global_offset_z
      - .offset:         184
        .size:           2
        .value_kind:     hidden_grid_dims
      - .offset:         240
        .size:           4
        .value_kind:     hidden_dynamic_lds_size
    .group_segment_fixed_size: 0
    .kernarg_segment_align: 8
    .kernarg_segment_size: 376
    .language:       OpenCL C
    .language_version:
      - 2
      - 0
    .max_flat_workgroup_size: 512
    .name:           _Z10fwd_kernel4Args
    .private_segment_fixed_size: 0
    .sgpr_count:     106
    .sgpr_spill_count: 0
    .symbol:         _Z10fwd_kernel4Args.kd
    .uniform_work_group_size: 1
    .uses_dynamic_stack: false
    .vgpr_count:     256
    .vgpr_spill_count: 0
    .wavefront_size: 64
